# LDS-DMA loads of all four GEMM K-loops converted to SGPR-base + 32-bit VGPR offset form (drops 16 VALU 64-bit adds per iteration from the load segments)
# speedup vs baseline: 1.0036x; 1.0035x over previous
; #define PG8_STAGE(bufoff, gbase, voff) do { _Pragma("unroll") for (int _i = 0; _i < 2; ++_i) \
;         __builtin_amdgcn_global_load_lds((const unsigned*)((const char*)(gbase) + (voff)[_i]), (LAS unsigned*)(lds + (bufoff) + ldsw + _i * 8192), 16, 0, 0); } while (0)
; #define PG8_LDA(dst, b, h) do { _Pragma("unroll") for (int m = 0; m < 4; ++m) _Pragma("unroll") for (int k = 0; k < 2; ++k) dst[m][k] = *(const LAS bf16x8*)(lds + PG8_SA(b, h) + aoff + m * 2048 + k * 1024); } while (0)
; #define PG8_LDB(dst, b, h) do { _Pragma("unroll") for (int n = 0; n < 2; ++n) _Pragma("unroll") for (int k = 0; k < 2; ++k) dst[n][k] = *(const LAS bf16x8*)(lds + PG8_SB(b, h) + boff + n * 2048 + k * 1024); } while (0)
; #define PG8_WAIT_V(n) asm volatile("s_waitcnt vmcnt(" #n ")" ::: "memory")
; #define PG8_WAIT_L(n) asm volatile("s_waitcnt lgkmcnt(" #n ")" ::: "memory")
; #define PG8_BAR __builtin_amdgcn_s_barrier()
; #define PG8_SCHED __builtin_amdgcn_sched_barrier(0)
; template <class Epi, class Sched, int KC, bool ALIGN_EPI = false, bool SP2 = false, bool ATILED = false>
; __device__ __forceinline__ void gemm_phase(LAS unsigned char* lds, const Gemm g, const Sched& S, const Epi& E, int wave_s) {
;     ...
;     const unsigned ldsw = (unsigned)wid * 1024u;
;     const int aoff = lds_byte(wr * 64 + fr, fq * 8), boff = lds_byte(wc * 32 + fr, fq * 8);
;     ...
;         for (int t = 0; t < nt; t += 2) {
;             const bool last = (t == nt - 2);
;             const char* a1 = cA + PG8_AOFF(t + 1);
;             const char* a2 = last ? nA : cA + PG8_AOFF(t + 2); const char* b2 = last ? nB : cB + (size_t)(t + 2) * kstep;
;             const char* a3 = a2 + kstep; const char* b3 = b2 + kstep;
;             if (last && has_next) S.a_ready(nxt);
;             if constexpr (SP2) {
;             PG8_LDB(B0, 0, 0); PG8_LDB(B1, 0, 1); PG8_SCHED; PG8_LDA(At, 0, 0); PG8_STAGE(PG8_SA(1, 1), a1 + hstepA, voffA);
;             PG8_WAIT_V(8); PG8_WAIT_L(0); PG8_BAR; PG8_MMA(0, 0, At, B0); PG8_MMA(0, 1, At, B1); PG8_BAR; PG8_SCHED;
;             PG8_LDA(At, 0, 1); PG8_STAGE(PG8_SB(0, 0), b2, voffB); PG8_STAGE(PG8_SB(0, 1), b2 + hstepB, voffB); PG8_STAGE(PG8_SA(0, 0), a2, voffA);
;             PG8_WAIT_V(8); PG8_WAIT_L(0); PG8_BAR; PG8_MMA(1, 0, At, B0); PG8_MMA(1, 1, At, B1); PG8_BAR; PG8_SCHED;
.LBB0_233:
	s_add_i32 s30, s58, 0xffc00000
	s_and_b32 s30, s30, 0x3800000
	s_and_b32 s31, s28, 0x100
	s_or_b32 s59, s31, s30
	s_and_b32 s34, s58, 0x7800000
	s_add_u32 s30, s28, 0x100
	s_addc_u32 s31, s29, 0
	s_and_b32 s35, s30, 0x100
	s_or_b32 s34, s34, s35
	s_add_u32 s34, s26, s34
	s_addc_u32 s35, s27, 0
	s_add_u32 s28, s55, s28
	s_addc_u32 s29, s56, s29
	s_add_i32 s62, 0, 0x10000
	s_cmp_eq_u32 s57, 28
	s_cselect_b32 s35, s19, s35
	s_cselect_b32 s34, s53, s34
	v_add_u32_e32 v139, s62, v163
	s_cselect_b32 s29, s17, s29
	s_cselect_b32 s28, s54, s28
	s_add_i32 s63, 0, 0x14000
	ds_read_b128 v[152:155], v139
	ds_read_b128 v[156:159], v139 offset:1024
	ds_read_b128 v[168:171], v139 offset:2048
	ds_read_b128 v[172:175], v139 offset:3072
	v_add_u32_e32 v139, s63, v163
	ds_read_b128 v[176:179], v139
	ds_read_b128 v[180:183], v139 offset:1024
	ds_read_b128 v[184:187], v139 offset:2048
	ds_read_b128 v[188:191], v139 offset:3072
	s_add_u32 s59, s26, s59
	s_addc_u32 s61, s27, 0
	s_add_u32 s60, s59, 0x10080
	s_addc_u32 s61, s61, 0
	s_add_i32 m0, s44, 0xc000
	ds_read_b128 v[198:201], v166
	ds_read_b128 v[202:205], v166 offset:1024
	ds_read_b128 v[206:209], v166 offset:2048
	ds_read_b128 v[210:213], v166 offset:3072
	ds_read_b128 v[214:217], v166 offset:4096
	ds_read_b128 v[218:221], v166 offset:5120
	ds_read_b128 v[222:225], v166 offset:6144
	ds_read_b128 v[226:229], v166 offset:7168
	global_load_lds_dwordx4 v136, s[60:61]
	s_add_i32 m0, s44, 0xe000
	s_nop 0
	global_load_lds_dwordx4 v132, s[60:61]
	s_waitcnt vmcnt(8)
	s_waitcnt lgkmcnt(0)
	s_barrier
	s_setprio 1
	s_waitcnt lgkmcnt(0)
	v_mfma_f32_16x16x32_bf16 v[122:125], v[152:155], v[198:201], v[122:125]
	v_mfma_f32_16x16x32_bf16 v[114:117], v[168:171], v[198:201], v[114:117]
	v_mfma_f32_16x16x32_bf16 v[106:109], v[152:155], v[206:209], v[106:109]
	v_mfma_f32_16x16x32_bf16 v[98:101], v[168:171], v[206:209], v[98:101]
	v_mfma_f32_16x16x32_bf16 v[90:93], v[152:155], v[214:217], v[90:93]
	v_mfma_f32_16x16x32_bf16 v[82:85], v[168:171], v[214:217], v[82:85]
	v_mfma_f32_16x16x32_bf16 v[74:77], v[152:155], v[222:225], v[74:77]
	v_mfma_f32_16x16x32_bf16 v[66:69], v[168:171], v[222:225], v[66:69]
	v_mfma_f32_16x16x32_bf16 v[122:125], v[156:159], v[202:205], v[122:125]
	v_mfma_f32_16x16x32_bf16 v[114:117], v[172:175], v[202:205], v[114:117]
	v_mfma_f32_16x16x32_bf16 v[106:109], v[156:159], v[210:213], v[106:109]
	v_mfma_f32_16x16x32_bf16 v[98:101], v[172:175], v[210:213], v[98:101]
	v_mfma_f32_16x16x32_bf16 v[90:93], v[156:159], v[218:221], v[90:93]
	v_mfma_f32_16x16x32_bf16 v[82:85], v[172:175], v[218:221], v[82:85]
	v_mfma_f32_16x16x32_bf16 v[74:77], v[156:159], v[226:229], v[74:77]
	v_mfma_f32_16x16x32_bf16 v[66:69], v[172:175], v[226:229], v[66:69]
	s_setprio 0
	s_setprio 1
	v_mfma_f32_16x16x32_bf16 v[126:129], v[176:179], v[198:201], v[126:129]
	v_mfma_f32_16x16x32_bf16 v[118:121], v[184:187], v[198:201], v[118:121]
	v_mfma_f32_16x16x32_bf16 v[110:113], v[176:179], v[206:209], v[110:113]
	v_mfma_f32_16x16x32_bf16 v[102:105], v[184:187], v[206:209], v[102:105]
	v_mfma_f32_16x16x32_bf16 v[94:97], v[176:179], v[214:217], v[94:97]
	v_mfma_f32_16x16x32_bf16 v[86:89], v[184:187], v[214:217], v[86:89]
	v_mfma_f32_16x16x32_bf16 v[78:81], v[176:179], v[222:225], v[78:81]
	v_mfma_f32_16x16x32_bf16 v[70:73], v[184:187], v[222:225], v[70:73]
	v_mfma_f32_16x16x32_bf16 v[126:129], v[180:183], v[202:205], v[126:129]
	v_mfma_f32_16x16x32_bf16 v[118:121], v[188:191], v[202:205], v[118:121]
	v_mfma_f32_16x16x32_bf16 v[110:113], v[180:183], v[210:213], v[110:113]
	v_mfma_f32_16x16x32_bf16 v[102:105], v[188:191], v[210:213], v[102:105]
	v_mfma_f32_16x16x32_bf16 v[94:97], v[180:183], v[218:221], v[94:97]
	v_mfma_f32_16x16x32_bf16 v[86:89], v[188:191], v[218:221], v[86:89]
	v_mfma_f32_16x16x32_bf16 v[78:81], v[180:183], v[226:229], v[78:81]
	v_mfma_f32_16x16x32_bf16 v[70:73], v[188:191], v[226:229], v[70:73]
	s_setprio 0
	s_barrier
	s_add_u32 s100, s34, 0x80
	s_addc_u32 s101, s35, 0
	s_add_i32 s59, s62, s38
	s_mov_b32 m0, s59
	ds_read_b128 v[198:201], v166 offset:16384
	ds_read_b128 v[202:205], v166 offset:17408
	ds_read_b128 v[206:209], v166 offset:18432
	ds_read_b128 v[210:213], v166 offset:19456
	ds_read_b128 v[214:217], v166 offset:20480
	ds_read_b128 v[218:221], v166 offset:21504
	ds_read_b128 v[222:225], v166 offset:22528
	ds_read_b128 v[226:229], v166 offset:23552
	global_load_lds_dwordx4 v134, s[28:29]
	s_add_i32 m0, s59, 0x2000
	s_add_u32 s60, s28, 0x80000
	s_addc_u32 s61, s29, 0
	s_add_i32 s59, s63, s38
	global_load_lds_dwordx4 v130, s[28:29]
	s_mov_b32 m0, s59
	s_nop 0
	global_load_lds_dwordx4 v134, s[60:61]
	s_add_i32 m0, s59, 0x2000
	s_nop 0
	global_load_lds_dwordx4 v130, s[60:61]
	s_mov_b32 m0, s44
	s_nop 0
	global_load_lds_dwordx4 v136, s[34:35]
	s_mov_b32 m0, s45
	s_nop 0
	global_load_lds_dwordx4 v132, s[34:35]
	s_waitcnt vmcnt(8)
	s_waitcnt lgkmcnt(0)
	s_barrier
; #define PG8_STAGE(bufoff, gbase, voff) do { _Pragma("unroll") for (int _i = 0; _i < 2; ++_i) \
;         __builtin_amdgcn_global_load_lds((const unsigned*)((const char*)(gbase) + (voff)[_i]), (LAS unsigned*)(lds + (bufoff) + ldsw + _i * 8192), 16, 0, 0); } while (0)
; #define PG8_LDA(dst, b, h) do { _Pragma("unroll") for (int m = 0; m < 4; ++m) _Pragma("unroll") for (int k = 0; k < 2; ++k) dst[m][k] = *(const LAS bf16x8*)(lds + PG8_SA(b, h) + aoff + m * 2048 + k * 1024); } while (0)
; #define PG8_LDB(dst, b, h) do { _Pragma("unroll") for (int n = 0; n < 2; ++n) _Pragma("unroll") for (int k = 0; k < 2; ++k) dst[n][k] = *(const LAS bf16x8*)(lds + PG8_SB(b, h) + boff + n * 2048 + k * 1024); } while (0)
; #define PG8_MMA(ai, bj, At, Bt) do { __builtin_amdgcn_s_setprio(1); _Pragma("unroll") for (int m = 0; m < 4; ++m) _Pragma("unroll") for (int n = 0; n < 2; ++n) _Pragma("unroll") for (int k = 0; k < 2; ++k) \
;         acc[ai][bj][m][n] = __builtin_amdgcn_mfma_f32_16x16x32_bf16(Bt[n][k], At[m][k], acc[ai][bj][m][n], 0, 0, 0); __builtin_amdgcn_s_setprio(0); } while (0)
; #define PG8_WAIT_V(n) asm volatile("s_waitcnt vmcnt(" #n ")" ::: "memory")
; #define PG8_WAIT_L(n) asm volatile("s_waitcnt lgkmcnt(" #n ")" ::: "memory")
; #define PG8_BAR __builtin_amdgcn_s_barrier()
; #define PG8_SCHED __builtin_amdgcn_sched_barrier(0)
; template <class Epi, class Sched, int KC, bool ALIGN_EPI = false, bool SP2 = false, bool ATILED = false>
; __device__ __forceinline__ void gemm_phase(LAS unsigned char* lds, const Gemm g, const Sched& S, const Epi& E, int wave_s) {
;     ...
;             PG8_WAIT_V(8); PG8_WAIT_L(0); PG8_BAR; PG8_MMA(1, 0, At, B0); PG8_MMA(1, 1, At, B1); PG8_BAR; PG8_SCHED;
;             PG8_LDB(B0, 1, 0); PG8_LDB(B1, 1, 1); PG8_SCHED; PG8_LDA(At, 1, 0); PG8_STAGE(PG8_SA(0, 1), a2 + hstepA, voffA);
;             PG8_WAIT_V(8); PG8_WAIT_L(0); PG8_BAR; PG8_MMA(0, 0, At, B0); PG8_MMA(0, 1, At, B1); PG8_BAR; PG8_SCHED;
	s_setprio 1
	s_waitcnt lgkmcnt(0)
	v_mfma_f32_16x16x32_bf16 v[58:61], v[152:155], v[198:201], v[58:61]
	v_mfma_f32_16x16x32_bf16 v[50:53], v[168:171], v[198:201], v[50:53]
	v_mfma_f32_16x16x32_bf16 v[42:45], v[152:155], v[206:209], v[42:45]
	v_mfma_f32_16x16x32_bf16 v[34:37], v[168:171], v[206:209], v[34:37]
	v_mfma_f32_16x16x32_bf16 v[26:29], v[152:155], v[214:217], v[26:29]
	v_mfma_f32_16x16x32_bf16 v[18:21], v[168:171], v[214:217], v[18:21]
	v_mfma_f32_16x16x32_bf16 v[10:13], v[152:155], v[222:225], v[10:13]
	v_mfma_f32_16x16x32_bf16 v[6:9], v[168:171], v[222:225], v[6:9]
	v_mfma_f32_16x16x32_bf16 v[58:61], v[156:159], v[202:205], v[58:61]
	v_mfma_f32_16x16x32_bf16 v[50:53], v[172:175], v[202:205], v[50:53]
	v_mfma_f32_16x16x32_bf16 v[42:45], v[156:159], v[210:213], v[42:45]
	v_mfma_f32_16x16x32_bf16 v[34:37], v[172:175], v[210:213], v[34:37]
	v_mfma_f32_16x16x32_bf16 v[26:29], v[156:159], v[218:221], v[26:29]
	v_mfma_f32_16x16x32_bf16 v[18:21], v[172:175], v[218:221], v[18:21]
	v_mfma_f32_16x16x32_bf16 v[10:13], v[156:159], v[226:229], v[10:13]
	v_mfma_f32_16x16x32_bf16 v[6:9], v[172:175], v[226:229], v[6:9]
	s_setprio 0
	s_setprio 1
	v_mfma_f32_16x16x32_bf16 v[62:65], v[176:179], v[198:201], v[62:65]
	v_mfma_f32_16x16x32_bf16 v[54:57], v[184:187], v[198:201], v[54:57]
	v_mfma_f32_16x16x32_bf16 v[46:49], v[176:179], v[206:209], v[46:49]
	v_mfma_f32_16x16x32_bf16 v[38:41], v[184:187], v[206:209], v[38:41]
	v_mfma_f32_16x16x32_bf16 v[30:33], v[176:179], v[214:217], v[30:33]
	v_mfma_f32_16x16x32_bf16 v[22:25], v[184:187], v[214:217], v[22:25]
	v_mfma_f32_16x16x32_bf16 v[14:17], v[176:179], v[222:225], v[14:17]
	v_mfma_f32_16x16x32_bf16 v[2:5], v[184:187], v[222:225], v[2:5]
	v_mfma_f32_16x16x32_bf16 v[62:65], v[180:183], v[202:205], v[62:65]
	v_mfma_f32_16x16x32_bf16 v[54:57], v[188:191], v[202:205], v[54:57]
	v_mfma_f32_16x16x32_bf16 v[46:49], v[180:183], v[210:213], v[46:49]
	v_mfma_f32_16x16x32_bf16 v[38:41], v[188:191], v[210:213], v[38:41]
	v_mfma_f32_16x16x32_bf16 v[30:33], v[180:183], v[218:221], v[30:33]
	v_mfma_f32_16x16x32_bf16 v[22:25], v[188:191], v[218:221], v[22:25]
	v_mfma_f32_16x16x32_bf16 v[14:17], v[180:183], v[226:229], v[14:17]
	v_mfma_f32_16x16x32_bf16 v[2:5], v[188:191], v[226:229], v[2:5]
	s_setprio 0
	s_barrier
	s_add_i32 s59, 0, 0x18000
	v_add_u32_e32 v139, s59, v163
	s_add_i32 s60, 0, 0x1c000
	ds_read_b128 v[152:155], v139
	ds_read_b128 v[156:159], v139 offset:1024
	ds_read_b128 v[168:171], v139 offset:2048
	ds_read_b128 v[172:175], v139 offset:3072
	v_add_u32_e32 v139, s60, v163
	ds_read_b128 v[176:179], v139
	ds_read_b128 v[180:183], v139 offset:1024
	ds_read_b128 v[184:187], v139 offset:2048
	ds_read_b128 v[188:191], v139 offset:3072
	s_add_u32 s34, s34, 0x10000
	s_addc_u32 s35, s35, 0
	s_mov_b32 m0, s46
	ds_read_b128 v[198:201], v166 offset:32768
	ds_read_b128 v[202:205], v166 offset:33792
	ds_read_b128 v[206:209], v166 offset:34816
	ds_read_b128 v[210:213], v166 offset:35840
	ds_read_b128 v[214:217], v166 offset:36864
	ds_read_b128 v[218:221], v166 offset:37888
	ds_read_b128 v[222:225], v166 offset:38912
	ds_read_b128 v[226:229], v166 offset:39936
	global_load_lds_dwordx4 v136, s[34:35]
	s_mov_b32 m0, s47
	s_nop 0
	global_load_lds_dwordx4 v132, s[34:35]
	s_waitcnt vmcnt(8)
	s_waitcnt lgkmcnt(0)
	s_barrier
	s_setprio 1
	s_waitcnt lgkmcnt(0)
	v_mfma_f32_16x16x32_bf16 v[122:125], v[152:155], v[198:201], v[122:125]
	v_mfma_f32_16x16x32_bf16 v[114:117], v[168:171], v[198:201], v[114:117]
	v_mfma_f32_16x16x32_bf16 v[106:109], v[152:155], v[206:209], v[106:109]
	v_mfma_f32_16x16x32_bf16 v[98:101], v[168:171], v[206:209], v[98:101]
	v_mfma_f32_16x16x32_bf16 v[90:93], v[152:155], v[214:217], v[90:93]
	v_mfma_f32_16x16x32_bf16 v[82:85], v[168:171], v[214:217], v[82:85]
	v_mfma_f32_16x16x32_bf16 v[74:77], v[152:155], v[222:225], v[74:77]
	v_mfma_f32_16x16x32_bf16 v[66:69], v[168:171], v[222:225], v[66:69]
	v_mfma_f32_16x16x32_bf16 v[122:125], v[156:159], v[202:205], v[122:125]
	v_mfma_f32_16x16x32_bf16 v[114:117], v[172:175], v[202:205], v[114:117]
	v_mfma_f32_16x16x32_bf16 v[106:109], v[156:159], v[210:213], v[106:109]
	v_mfma_f32_16x16x32_bf16 v[98:101], v[172:175], v[210:213], v[98:101]
	v_mfma_f32_16x16x32_bf16 v[90:93], v[156:159], v[218:221], v[90:93]
	v_mfma_f32_16x16x32_bf16 v[82:85], v[172:175], v[218:221], v[82:85]
	v_mfma_f32_16x16x32_bf16 v[74:77], v[156:159], v[226:229], v[74:77]
	v_mfma_f32_16x16x32_bf16 v[66:69], v[172:175], v[226:229], v[66:69]
	s_setprio 0
	s_setprio 1
	v_mfma_f32_16x16x32_bf16 v[126:129], v[176:179], v[198:201], v[126:129]
	v_mfma_f32_16x16x32_bf16 v[118:121], v[184:187], v[198:201], v[118:121]
	v_mfma_f32_16x16x32_bf16 v[110:113], v[176:179], v[206:209], v[110:113]
	v_mfma_f32_16x16x32_bf16 v[102:105], v[184:187], v[206:209], v[102:105]
	v_mfma_f32_16x16x32_bf16 v[94:97], v[176:179], v[214:217], v[94:97]
	v_mfma_f32_16x16x32_bf16 v[86:89], v[184:187], v[214:217], v[86:89]
	v_mfma_f32_16x16x32_bf16 v[78:81], v[176:179], v[222:225], v[78:81]
	v_mfma_f32_16x16x32_bf16 v[70:73], v[184:187], v[222:225], v[70:73]
	v_mfma_f32_16x16x32_bf16 v[126:129], v[180:183], v[202:205], v[126:129]
	v_mfma_f32_16x16x32_bf16 v[118:121], v[188:191], v[202:205], v[118:121]
	v_mfma_f32_16x16x32_bf16 v[110:113], v[180:183], v[210:213], v[110:113]
	v_mfma_f32_16x16x32_bf16 v[102:105], v[188:191], v[210:213], v[102:105]
	v_mfma_f32_16x16x32_bf16 v[94:97], v[180:183], v[218:221], v[94:97]
	v_mfma_f32_16x16x32_bf16 v[86:89], v[188:191], v[218:221], v[86:89]
	v_mfma_f32_16x16x32_bf16 v[78:81], v[180:183], v[226:229], v[78:81]
	v_mfma_f32_16x16x32_bf16 v[70:73], v[188:191], v[226:229], v[70:73]
	s_setprio 0
	s_barrier
; #define PG8_STAGE(bufoff, gbase, voff) do { _Pragma("unroll") for (int _i = 0; _i < 2; ++_i) \
;         __builtin_amdgcn_global_load_lds((const unsigned*)((const char*)(gbase) + (voff)[_i]), (LAS unsigned*)(lds + (bufoff) + ldsw + _i * 8192), 16, 0, 0); } while (0)
; #define PG8_LDA(dst, b, h) do { _Pragma("unroll") for (int m = 0; m < 4; ++m) _Pragma("unroll") for (int k = 0; k < 2; ++k) dst[m][k] = *(const LAS bf16x8*)(lds + PG8_SA(b, h) + aoff + m * 2048 + k * 1024); } while (0)
; #define PG8_BAR __builtin_amdgcn_s_barrier()
; template <class Epi, class Sched, int KC, bool ALIGN_EPI = false, bool SP2 = false, bool ATILED = false>
; __device__ __forceinline__ void gemm_phase(LAS unsigned char* lds, const Gemm g, const Sched& S, const Epi& E, int wave_s) {
;     ...
;             PG8_LDA(At, 1, 1); PG8_STAGE(PG8_SB(1, 0), b3, voffB); PG8_STAGE(PG8_SB(1, 1), b3 + hstepB, voffB); PG8_STAGE(PG8_SA(1, 0), a3, voffA);
;             PG8_WAIT_V(8); PG8_WAIT_L(0); PG8_BAR; PG8_MMA(1, 0, At, B0); PG8_MMA(1, 1, At, B1); PG8_BAR; PG8_SCHED;
;             } else {
;             PG8_LDB(B0, 0, 0); PG8_SCHED; PG8_LDA(At, 0, 0); PG8_STAGE(PG8_SA(1, 1), a1 + hstepA, voffA);
;             PG8_WAIT_L(8); PG8_BAR; PG8_WAIT_L(0); PG8_MMA(0, 0, At, B0); PG8_BAR; PG8_SCHED;
;             PG8_LDB(B1, 0, 1); PG8_STAGE(PG8_SB(0, 0), b2, voffB);
;             PG8_BAR; PG8_WAIT_L(0); PG8_MMA(0, 1, At, B1); PG8_BAR;
;             PG8_LDA(At, 0, 1); PG8_STAGE(PG8_SA(0, 0), a2, voffA);
;             PG8_BAR; PG8_WAIT_L(0); PG8_MMA(1, 0, At, B0); PG8_BAR; PG8_SCHED;
;             PG8_STAGE(PG8_SB(0, 1), b2 + hstepB, voffB);
;             PG8_WAIT_V(6); PG8_BAR; PG8_MMA(1, 1, At, B1); PG8_BAR;
;             PG8_LDB(B0, 1, 0); PG8_SCHED; PG8_LDA(At, 1, 0); PG8_STAGE(PG8_SA(0, 1), a2 + hstepA, voffA);
;             PG8_WAIT_L(8); PG8_BAR; PG8_WAIT_L(0); PG8_MMA(0, 0, At, B0); PG8_BAR; PG8_SCHED;
;             PG8_LDB(B1, 1, 1); PG8_STAGE(PG8_SB(1, 0), b3, voffB);
;             PG8_BAR; PG8_WAIT_L(0); PG8_MMA(0, 1, At, B1); PG8_BAR;
;             PG8_LDA(At, 1, 1); PG8_STAGE(PG8_SA(1, 0), a3, voffA);
;             PG8_BAR; PG8_WAIT_L(0); PG8_MMA(1, 0, At, B0); PG8_BAR; PG8_SCHED;
;             PG8_STAGE(PG8_SB(1, 1), b3 + hstepB, voffB);
;             PG8_WAIT_V(6); PG8_BAR; PG8_MMA(1, 1, At, B1); PG8_BAR;
;             }
;         }
;         if constexpr (ALIGN_EPI) { if (wr == 0) PG8_BAR; }
	s_add_u32 s98, s28, 0x80
	s_addc_u32 s99, s29, 0
	s_add_i32 s34, s59, s38
	s_mov_b32 m0, s34
	ds_read_b128 v[198:201], v166 offset:49152
	ds_read_b128 v[202:205], v166 offset:50176
	ds_read_b128 v[206:209], v166 offset:51200
	ds_read_b128 v[210:213], v166 offset:52224
	ds_read_b128 v[214:217], v166 offset:53248
	ds_read_b128 v[218:221], v166 offset:54272
	ds_read_b128 v[222:225], v166 offset:55296
	ds_read_b128 v[226:229], v166 offset:56320
	global_load_lds_dwordx4 v134, s[98:99]
	s_add_i32 m0, s34, 0x2000
	s_add_u32 s28, s28, 0x80080
	s_addc_u32 s29, s29, 0
	s_add_i32 s34, s60, s38
	global_load_lds_dwordx4 v130, s[98:99]
	s_mov_b32 m0, s34
	s_nop 0
	global_load_lds_dwordx4 v134, s[28:29]
	s_add_i32 m0, s34, 0x2000
	s_nop 0
	global_load_lds_dwordx4 v130, s[28:29]
	s_mov_b32 m0, s48
	s_nop 0
	global_load_lds_dwordx4 v136, s[100:101]
	s_mov_b32 m0, s49
	s_nop 0
	global_load_lds_dwordx4 v132, s[100:101]
	s_waitcnt vmcnt(8)
	s_waitcnt lgkmcnt(0)
	s_barrier
	s_setprio 1
	s_waitcnt lgkmcnt(0)
	v_mfma_f32_16x16x32_bf16 v[58:61], v[152:155], v[198:201], v[58:61]
	v_mfma_f32_16x16x32_bf16 v[50:53], v[168:171], v[198:201], v[50:53]
	v_mfma_f32_16x16x32_bf16 v[42:45], v[152:155], v[206:209], v[42:45]
	v_mfma_f32_16x16x32_bf16 v[34:37], v[168:171], v[206:209], v[34:37]
	v_mfma_f32_16x16x32_bf16 v[26:29], v[152:155], v[214:217], v[26:29]
	v_mfma_f32_16x16x32_bf16 v[18:21], v[168:171], v[214:217], v[18:21]
	v_mfma_f32_16x16x32_bf16 v[10:13], v[152:155], v[222:225], v[10:13]
	v_mfma_f32_16x16x32_bf16 v[6:9], v[168:171], v[222:225], v[6:9]
	v_mfma_f32_16x16x32_bf16 v[58:61], v[156:159], v[202:205], v[58:61]
	v_mfma_f32_16x16x32_bf16 v[50:53], v[172:175], v[202:205], v[50:53]
	v_mfma_f32_16x16x32_bf16 v[42:45], v[156:159], v[210:213], v[42:45]
	v_mfma_f32_16x16x32_bf16 v[34:37], v[172:175], v[210:213], v[34:37]
	v_mfma_f32_16x16x32_bf16 v[26:29], v[156:159], v[218:221], v[26:29]
	v_mfma_f32_16x16x32_bf16 v[18:21], v[172:175], v[218:221], v[18:21]
	v_mfma_f32_16x16x32_bf16 v[10:13], v[156:159], v[226:229], v[10:13]
	v_mfma_f32_16x16x32_bf16 v[6:9], v[172:175], v[226:229], v[6:9]
	s_setprio 0
	s_setprio 1
	v_mfma_f32_16x16x32_bf16 v[62:65], v[176:179], v[198:201], v[62:65]
	v_mfma_f32_16x16x32_bf16 v[54:57], v[184:187], v[198:201], v[54:57]
	v_mfma_f32_16x16x32_bf16 v[46:49], v[176:179], v[206:209], v[46:49]
	v_mfma_f32_16x16x32_bf16 v[38:41], v[184:187], v[206:209], v[38:41]
	v_mfma_f32_16x16x32_bf16 v[30:33], v[176:179], v[214:217], v[30:33]
	v_mfma_f32_16x16x32_bf16 v[22:25], v[184:187], v[214:217], v[22:25]
	v_mfma_f32_16x16x32_bf16 v[14:17], v[176:179], v[222:225], v[14:17]
	v_mfma_f32_16x16x32_bf16 v[2:5], v[184:187], v[222:225], v[2:5]
	v_mfma_f32_16x16x32_bf16 v[62:65], v[180:183], v[202:205], v[62:65]
	v_mfma_f32_16x16x32_bf16 v[54:57], v[188:191], v[202:205], v[54:57]
	v_mfma_f32_16x16x32_bf16 v[46:49], v[180:183], v[210:213], v[46:49]
	v_mfma_f32_16x16x32_bf16 v[38:41], v[188:191], v[210:213], v[38:41]
	v_mfma_f32_16x16x32_bf16 v[30:33], v[180:183], v[218:221], v[30:33]
	v_mfma_f32_16x16x32_bf16 v[22:25], v[188:191], v[218:221], v[22:25]
	v_mfma_f32_16x16x32_bf16 v[14:17], v[180:183], v[226:229], v[14:17]
	v_mfma_f32_16x16x32_bf16 v[2:5], v[188:191], v[226:229], v[2:5]
	s_setprio 0
	s_barrier
	s_add_i32 s57, s57, 2
	s_add_i32 s58, s58, 0x400000
	s_cmp_gt_u32 s57, 29
	s_mov_b64 s[28:29], s[30:31]
	s_cbranch_scc0 .LBB0_233
	s_and_b64 vcc, exec, s[14:15]
	s_cbranch_vccz .LBB0_236
	s_barrier

; #define PG8_STAGE(bufoff, gbase, voff) do { _Pragma("unroll") for (int _i = 0; _i < 2; ++_i) \
;         __builtin_amdgcn_global_load_lds((const unsigned*)((const char*)(gbase) + (voff)[_i]), (LAS unsigned*)(lds + (bufoff) + ldsw + _i * 8192), 16, 0, 0); } while (0)
; #define PG8_LDA(dst, b, h) do { _Pragma("unroll") for (int m = 0; m < 4; ++m) _Pragma("unroll") for (int k = 0; k < 2; ++k) dst[m][k] = *(const LAS bf16x8*)(lds + PG8_SA(b, h) + aoff + m * 2048 + k * 1024); } while (0)
; #define PG8_LDB(dst, b, h) do { _Pragma("unroll") for (int n = 0; n < 2; ++n) _Pragma("unroll") for (int k = 0; k < 2; ++k) dst[n][k] = *(const LAS bf16x8*)(lds + PG8_SB(b, h) + boff + n * 2048 + k * 1024); } while (0)
; #define PG8_MMA(ai, bj, At, Bt) do { __builtin_amdgcn_s_setprio(1); _Pragma("unroll") for (int m = 0; m < 4; ++m) _Pragma("unroll") for (int n = 0; n < 2; ++n) _Pragma("unroll") for (int k = 0; k < 2; ++k) \
;         acc[ai][bj][m][n] = __builtin_amdgcn_mfma_f32_16x16x32_bf16(Bt[n][k], At[m][k], acc[ai][bj][m][n], 0, 0, 0); __builtin_amdgcn_s_setprio(0); } while (0)
; #define PG8_WAIT_V(n) asm volatile("s_waitcnt vmcnt(" #n ")" ::: "memory")
; #define PG8_BAR __builtin_amdgcn_s_barrier()
; template <class Epi, class Sched, int KC, bool ALIGN_EPI = false, bool SP2 = false, bool ATILED = false>
; __device__ __forceinline__ void gemm_phase(LAS unsigned char* lds, const Gemm g, const Sched& S, const Epi& E, int wave_s) {
;     ...
;         for (int t = 0; t < nt; t += 2) {
;             const bool last = (t == nt - 2);
;             const char* a1 = cA + PG8_AOFF(t + 1);
;             const char* a2 = last ? nA : cA + PG8_AOFF(t + 2); const char* b2 = last ? nB : cB + (size_t)(t + 2) * kstep;
;             const char* a3 = a2 + kstep; const char* b3 = b2 + kstep;
;             if (last && has_next) S.a_ready(nxt);
;             if constexpr (SP2) {
;             PG8_LDB(B0, 0, 0); PG8_LDB(B1, 0, 1); PG8_SCHED; PG8_LDA(At, 0, 0); PG8_STAGE(PG8_SA(1, 1), a1 + hstepA, voffA);
;             PG8_WAIT_V(8); PG8_WAIT_L(0); PG8_BAR; PG8_MMA(0, 0, At, B0); PG8_MMA(0, 1, At, B1); PG8_BAR; PG8_SCHED;
;             PG8_LDA(At, 0, 1); PG8_STAGE(PG8_SB(0, 0), b2, voffB); PG8_STAGE(PG8_SB(0, 1), b2 + hstepB, voffB); PG8_STAGE(PG8_SA(0, 0), a2, voffA);
;             PG8_WAIT_V(8); PG8_WAIT_L(0); PG8_BAR; PG8_MMA(1, 0, At, B0); PG8_MMA(1, 1, At, B1); PG8_BAR; PG8_SCHED;
.LBB0_318:
	s_add_u32 s8, s20, 0x100
	s_addc_u32 s9, s21, 0
	s_add_i32 s53, 0, 0x10000
	s_cmpk_eq_i32 s52, 0x54
	s_cselect_b32 s25, s17, s9
	s_cselect_b32 s24, s16, s8
	s_cselect_b32 s23, s11, s51
	s_cselect_b32 s22, s10, s50
	s_add_i32 s54, 0, 0x14000
	v_add_u32_e32 v114, s53, v249
	v_add_u32_e32 v150, s54, v249
	ds_read_b128 v[82:85], v114
	ds_read_b128 v[94:97], v114 offset:1024
	ds_read_b128 v[106:109], v114 offset:2048
	ds_read_b128 v[114:117], v114 offset:3072
	ds_read_b128 v[130:133], v150
	ds_read_b128 v[134:137], v150 offset:1024
	ds_read_b128 v[146:149], v150 offset:2048
	ds_read_b128 v[150:153], v150 offset:3072
	s_add_i32 m0, s36, 0xc000
	ds_read_b128 v[154:157], v251
	ds_read_b128 v[166:169], v251 offset:1024
	ds_read_b128 v[170:173], v251 offset:2048
	ds_read_b128 v[174:177], v251 offset:3072
	ds_read_b128 v[178:181], v251 offset:4096
	ds_read_b128 v[182:185], v251 offset:5120
	ds_read_b128 v[186:189], v251 offset:6144
	ds_read_b128 v[194:197], v251 offset:7168
	global_load_lds_dwordx4 v204, s[20:21]
	s_add_i32 m0, s36, 0xe000
	s_nop 0
	global_load_lds_dwordx4 v202, s[20:21]
	s_waitcnt vmcnt(8)
	s_waitcnt lgkmcnt(0)
	s_barrier
	s_setprio 1
	s_waitcnt lgkmcnt(0)
	v_mfma_f32_16x16x32_bf16 v[162:165], v[82:85], v[154:157], v[162:165]
	v_mfma_f32_16x16x32_bf16 v[158:161], v[106:109], v[154:157], v[158:161]
	v_mfma_f32_16x16x32_bf16 v[126:129], v[82:85], v[170:173], v[126:129]
	v_mfma_f32_16x16x32_bf16 v[122:125], v[106:109], v[170:173], v[122:125]
	v_mfma_f32_16x16x32_bf16 v[102:105], v[82:85], v[178:181], v[102:105]
	v_mfma_f32_16x16x32_bf16 v[98:101], v[106:109], v[178:181], v[98:101]
	v_mfma_f32_16x16x32_bf16 v[78:81], v[82:85], v[186:189], v[78:81]
	v_mfma_f32_16x16x32_bf16 v[74:77], v[106:109], v[186:189], v[74:77]
	v_mfma_f32_16x16x32_bf16 v[162:165], v[94:97], v[166:169], v[162:165]
	v_mfma_f32_16x16x32_bf16 v[158:161], v[114:117], v[166:169], v[158:161]
	v_mfma_f32_16x16x32_bf16 v[126:129], v[94:97], v[174:177], v[126:129]
	v_mfma_f32_16x16x32_bf16 v[122:125], v[114:117], v[174:177], v[122:125]
	v_mfma_f32_16x16x32_bf16 v[102:105], v[94:97], v[182:185], v[102:105]
	v_mfma_f32_16x16x32_bf16 v[98:101], v[114:117], v[182:185], v[98:101]
	v_mfma_f32_16x16x32_bf16 v[78:81], v[94:97], v[194:197], v[78:81]
	v_mfma_f32_16x16x32_bf16 v[74:77], v[114:117], v[194:197], v[74:77]
	s_setprio 0
	s_setprio 1
	v_mfma_f32_16x16x32_bf16 v[142:145], v[130:133], v[154:157], v[142:145]
	v_mfma_f32_16x16x32_bf16 v[138:141], v[146:149], v[154:157], v[138:141]
	v_mfma_f32_16x16x32_bf16 v[118:121], v[130:133], v[170:173], v[118:121]
	v_mfma_f32_16x16x32_bf16 v[110:113], v[146:149], v[170:173], v[110:113]
	v_mfma_f32_16x16x32_bf16 v[90:93], v[130:133], v[178:181], v[90:93]
	v_mfma_f32_16x16x32_bf16 v[86:89], v[146:149], v[178:181], v[86:89]
	v_mfma_f32_16x16x32_bf16 v[70:73], v[130:133], v[186:189], v[70:73]
	v_mfma_f32_16x16x32_bf16 v[66:69], v[146:149], v[186:189], v[66:69]
	v_mfma_f32_16x16x32_bf16 v[142:145], v[134:137], v[166:169], v[142:145]
	v_mfma_f32_16x16x32_bf16 v[138:141], v[150:153], v[166:169], v[138:141]
	v_mfma_f32_16x16x32_bf16 v[118:121], v[134:137], v[174:177], v[118:121]
	v_mfma_f32_16x16x32_bf16 v[110:113], v[150:153], v[174:177], v[110:113]
	v_mfma_f32_16x16x32_bf16 v[90:93], v[134:137], v[182:185], v[90:93]
	v_mfma_f32_16x16x32_bf16 v[86:89], v[150:153], v[182:185], v[86:89]
	v_mfma_f32_16x16x32_bf16 v[70:73], v[134:137], v[194:197], v[70:73]
	v_mfma_f32_16x16x32_bf16 v[66:69], v[150:153], v[194:197], v[66:69]
	s_setprio 0
	s_barrier
	s_add_i32 s20, s53, s35
	s_mov_b32 m0, s20
	ds_read_b128 v[154:157], v251 offset:16384
	ds_read_b128 v[166:169], v251 offset:17408
	ds_read_b128 v[170:173], v251 offset:18432
	ds_read_b128 v[174:177], v251 offset:19456
	ds_read_b128 v[178:181], v251 offset:20480
	ds_read_b128 v[182:185], v251 offset:21504
	ds_read_b128 v[186:189], v251 offset:22528
	ds_read_b128 v[194:197], v251 offset:23552
	global_load_lds_dwordx4 v0, s[22:23]
	s_add_i32 m0, s20, 0x2000
	s_add_u32 s20, s22, 0x58000
	s_addc_u32 s21, s23, 0
	s_add_i32 s53, s54, s35
	global_load_lds_dwordx4 v198, s[22:23]
	s_mov_b32 m0, s53
	s_nop 0
	global_load_lds_dwordx4 v0, s[20:21]
	s_add_i32 m0, s53, 0x2000
	s_nop 0
	global_load_lds_dwordx4 v198, s[20:21]
	s_mov_b32 m0, s36
	s_nop 0
	global_load_lds_dwordx4 v190, s[24:25]
	s_mov_b32 m0, s37
	s_nop 0
	global_load_lds_dwordx4 v192, s[24:25]
	s_waitcnt vmcnt(8)
	s_waitcnt lgkmcnt(0)
	s_barrier
	s_setprio 1
	s_waitcnt lgkmcnt(0)
	v_mfma_f32_16x16x32_bf16 v[62:65], v[82:85], v[154:157], v[62:65]
	v_mfma_f32_16x16x32_bf16 v[58:61], v[106:109], v[154:157], v[58:61]
	v_mfma_f32_16x16x32_bf16 v[46:49], v[82:85], v[170:173], v[46:49]
	v_mfma_f32_16x16x32_bf16 v[42:45], v[106:109], v[170:173], v[42:45]
	v_mfma_f32_16x16x32_bf16 v[30:33], v[82:85], v[178:181], v[30:33]
	v_mfma_f32_16x16x32_bf16 v[26:29], v[106:109], v[178:181], v[26:29]
	v_mfma_f32_16x16x32_bf16 v[14:17], v[82:85], v[186:189], v[14:17]
	v_mfma_f32_16x16x32_bf16 v[10:13], v[106:109], v[186:189], v[10:13]
	v_mfma_f32_16x16x32_bf16 v[62:65], v[94:97], v[166:169], v[62:65]
	v_mfma_f32_16x16x32_bf16 v[58:61], v[114:117], v[166:169], v[58:61]
	v_mfma_f32_16x16x32_bf16 v[46:49], v[94:97], v[174:177], v[46:49]
	v_mfma_f32_16x16x32_bf16 v[42:45], v[114:117], v[174:177], v[42:45]
	v_mfma_f32_16x16x32_bf16 v[30:33], v[94:97], v[182:185], v[30:33]
	v_mfma_f32_16x16x32_bf16 v[26:29], v[114:117], v[182:185], v[26:29]
	v_mfma_f32_16x16x32_bf16 v[14:17], v[94:97], v[194:197], v[14:17]
	v_mfma_f32_16x16x32_bf16 v[10:13], v[114:117], v[194:197], v[10:13]
	s_setprio 0
	s_setprio 1
	v_mfma_f32_16x16x32_bf16 v[54:57], v[130:133], v[154:157], v[54:57]
	v_mfma_f32_16x16x32_bf16 v[50:53], v[146:149], v[154:157], v[50:53]
	v_mfma_f32_16x16x32_bf16 v[38:41], v[130:133], v[170:173], v[38:41]
	v_mfma_f32_16x16x32_bf16 v[34:37], v[146:149], v[170:173], v[34:37]
	v_mfma_f32_16x16x32_bf16 v[22:25], v[130:133], v[178:181], v[22:25]
	v_mfma_f32_16x16x32_bf16 v[18:21], v[146:149], v[178:181], v[18:21]
	v_mfma_f32_16x16x32_bf16 v[6:9], v[130:133], v[186:189], v[6:9]
	v_mfma_f32_16x16x32_bf16 v[2:5], v[146:149], v[186:189], v[2:5]
	v_mfma_f32_16x16x32_bf16 v[54:57], v[134:137], v[166:169], v[54:57]
	v_mfma_f32_16x16x32_bf16 v[50:53], v[150:153], v[166:169], v[50:53]
	v_mfma_f32_16x16x32_bf16 v[38:41], v[134:137], v[174:177], v[38:41]
	v_mfma_f32_16x16x32_bf16 v[34:37], v[150:153], v[174:177], v[34:37]
	v_mfma_f32_16x16x32_bf16 v[22:25], v[134:137], v[182:185], v[22:25]
	v_mfma_f32_16x16x32_bf16 v[18:21], v[150:153], v[182:185], v[18:21]
	v_mfma_f32_16x16x32_bf16 v[6:9], v[134:137], v[194:197], v[6:9]
	v_mfma_f32_16x16x32_bf16 v[2:5], v[150:153], v[194:197], v[2:5]
	s_setprio 0
	s_barrier
; #define PG8_STAGE(bufoff, gbase, voff) do { _Pragma("unroll") for (int _i = 0; _i < 2; ++_i) \
;         __builtin_amdgcn_global_load_lds((const unsigned*)((const char*)(gbase) + (voff)[_i]), (LAS unsigned*)(lds + (bufoff) + ldsw + _i * 8192), 16, 0, 0); } while (0)
; #define PG8_LDA(dst, b, h) do { _Pragma("unroll") for (int m = 0; m < 4; ++m) _Pragma("unroll") for (int k = 0; k < 2; ++k) dst[m][k] = *(const LAS bf16x8*)(lds + PG8_SA(b, h) + aoff + m * 2048 + k * 1024); } while (0)
; #define PG8_LDB(dst, b, h) do { _Pragma("unroll") for (int n = 0; n < 2; ++n) _Pragma("unroll") for (int k = 0; k < 2; ++k) dst[n][k] = *(const LAS bf16x8*)(lds + PG8_SB(b, h) + boff + n * 2048 + k * 1024); } while (0)
; #define PG8_MMA(ai, bj, At, Bt) do { __builtin_amdgcn_s_setprio(1); _Pragma("unroll") for (int m = 0; m < 4; ++m) _Pragma("unroll") for (int n = 0; n < 2; ++n) _Pragma("unroll") for (int k = 0; k < 2; ++k) \
;         acc[ai][bj][m][n] = __builtin_amdgcn_mfma_f32_16x16x32_bf16(Bt[n][k], At[m][k], acc[ai][bj][m][n], 0, 0, 0); __builtin_amdgcn_s_setprio(0); } while (0)
; #define PG8_WAIT_V(n) asm volatile("s_waitcnt vmcnt(" #n ")" ::: "memory")
; #define PG8_WAIT_L(n) asm volatile("s_waitcnt lgkmcnt(" #n ")" ::: "memory")
; #define PG8_BAR __builtin_amdgcn_s_barrier()
; #define PG8_SCHED __builtin_amdgcn_sched_barrier(0)
; template <class Epi, class Sched, int KC, bool ALIGN_EPI = false, bool SP2 = false, bool ATILED = false>
; __device__ __forceinline__ void gemm_phase(LAS unsigned char* lds, const Gemm g, const Sched& S, const Epi& E, int wave_s) {
;     ...
;             PG8_LDB(B0, 1, 0); PG8_LDB(B1, 1, 1); PG8_SCHED; PG8_LDA(At, 1, 0); PG8_STAGE(PG8_SA(0, 1), a2 + hstepA, voffA);
;             PG8_WAIT_V(8); PG8_WAIT_L(0); PG8_BAR; PG8_MMA(0, 0, At, B0); PG8_MMA(0, 1, At, B1); PG8_BAR; PG8_SCHED;
;             PG8_LDA(At, 1, 1); PG8_STAGE(PG8_SB(1, 0), b3, voffB); PG8_STAGE(PG8_SB(1, 1), b3 + hstepB, voffB); PG8_STAGE(PG8_SA(1, 0), a3, voffA);
;             PG8_WAIT_V(8); PG8_WAIT_L(0); PG8_BAR; PG8_MMA(1, 0, At, B0); PG8_MMA(1, 1, At, B1); PG8_BAR; PG8_SCHED;
	s_add_i32 s53, 0, 0x18000
	s_add_i32 s54, 0, 0x1c000
	v_add_u32_e32 v114, s53, v249
	v_add_u32_e32 v150, s54, v249
	ds_read_b128 v[82:85], v114
	ds_read_b128 v[94:97], v114 offset:1024
	ds_read_b128 v[106:109], v114 offset:2048
	ds_read_b128 v[114:117], v114 offset:3072
	ds_read_b128 v[130:133], v150
	ds_read_b128 v[134:137], v150 offset:1024
	ds_read_b128 v[146:149], v150 offset:2048
	ds_read_b128 v[150:153], v150 offset:3072
	s_add_u32 s20, s24, 0x160000
	s_addc_u32 s21, s25, 0
	s_mov_b32 m0, s38
	ds_read_b128 v[154:157], v251 offset:32768
	ds_read_b128 v[166:169], v251 offset:33792
	ds_read_b128 v[170:173], v251 offset:34816
	ds_read_b128 v[174:177], v251 offset:35840
	ds_read_b128 v[178:181], v251 offset:36864
	ds_read_b128 v[182:185], v251 offset:37888
	ds_read_b128 v[186:189], v251 offset:38912
	ds_read_b128 v[194:197], v251 offset:39936
	global_load_lds_dwordx4 v190, s[20:21]
	s_mov_b32 m0, s39
	s_nop 0
	global_load_lds_dwordx4 v192, s[20:21]
	s_waitcnt vmcnt(8)
	s_waitcnt lgkmcnt(0)
	s_barrier
	s_setprio 1
	s_waitcnt lgkmcnt(0)
	v_mfma_f32_16x16x32_bf16 v[162:165], v[82:85], v[154:157], v[162:165]
	v_mfma_f32_16x16x32_bf16 v[158:161], v[106:109], v[154:157], v[158:161]
	v_mfma_f32_16x16x32_bf16 v[126:129], v[82:85], v[170:173], v[126:129]
	v_mfma_f32_16x16x32_bf16 v[122:125], v[106:109], v[170:173], v[122:125]
	v_mfma_f32_16x16x32_bf16 v[102:105], v[82:85], v[178:181], v[102:105]
	v_mfma_f32_16x16x32_bf16 v[98:101], v[106:109], v[178:181], v[98:101]
	v_mfma_f32_16x16x32_bf16 v[78:81], v[82:85], v[186:189], v[78:81]
	v_mfma_f32_16x16x32_bf16 v[74:77], v[106:109], v[186:189], v[74:77]
	v_mfma_f32_16x16x32_bf16 v[162:165], v[94:97], v[166:169], v[162:165]
	v_mfma_f32_16x16x32_bf16 v[158:161], v[114:117], v[166:169], v[158:161]
	v_mfma_f32_16x16x32_bf16 v[126:129], v[94:97], v[174:177], v[126:129]
	v_mfma_f32_16x16x32_bf16 v[122:125], v[114:117], v[174:177], v[122:125]
	v_mfma_f32_16x16x32_bf16 v[102:105], v[94:97], v[182:185], v[102:105]
	v_mfma_f32_16x16x32_bf16 v[98:101], v[114:117], v[182:185], v[98:101]
	v_mfma_f32_16x16x32_bf16 v[78:81], v[94:97], v[194:197], v[78:81]
	v_mfma_f32_16x16x32_bf16 v[74:77], v[114:117], v[194:197], v[74:77]
	s_setprio 0
	s_setprio 1
	v_mfma_f32_16x16x32_bf16 v[142:145], v[130:133], v[154:157], v[142:145]
	v_mfma_f32_16x16x32_bf16 v[138:141], v[146:149], v[154:157], v[138:141]
	v_mfma_f32_16x16x32_bf16 v[118:121], v[130:133], v[170:173], v[118:121]
	v_mfma_f32_16x16x32_bf16 v[110:113], v[146:149], v[170:173], v[110:113]
	v_mfma_f32_16x16x32_bf16 v[90:93], v[130:133], v[178:181], v[90:93]
	v_mfma_f32_16x16x32_bf16 v[86:89], v[146:149], v[178:181], v[86:89]
	v_mfma_f32_16x16x32_bf16 v[70:73], v[130:133], v[186:189], v[70:73]
	v_mfma_f32_16x16x32_bf16 v[66:69], v[146:149], v[186:189], v[66:69]
	v_mfma_f32_16x16x32_bf16 v[142:145], v[134:137], v[166:169], v[142:145]
	v_mfma_f32_16x16x32_bf16 v[138:141], v[150:153], v[166:169], v[138:141]
	v_mfma_f32_16x16x32_bf16 v[118:121], v[134:137], v[174:177], v[118:121]
	v_mfma_f32_16x16x32_bf16 v[110:113], v[150:153], v[174:177], v[110:113]
	v_mfma_f32_16x16x32_bf16 v[90:93], v[134:137], v[182:185], v[90:93]
	v_mfma_f32_16x16x32_bf16 v[86:89], v[150:153], v[182:185], v[86:89]
	v_mfma_f32_16x16x32_bf16 v[70:73], v[134:137], v[194:197], v[70:73]
	v_mfma_f32_16x16x32_bf16 v[66:69], v[150:153], v[194:197], v[66:69]
	s_setprio 0
	s_barrier
	s_add_u32 s98, s22, 0x80
	s_addc_u32 s99, s23, 0
	s_add_u32 s100, s24, 0x80
	s_addc_u32 s101, s25, 0
	s_add_i32 s20, s53, s35
	s_mov_b32 m0, s20
	ds_read_b128 v[154:157], v251 offset:49152
	ds_read_b128 v[166:169], v251 offset:50176
	ds_read_b128 v[170:173], v251 offset:51200
	ds_read_b128 v[174:177], v251 offset:52224
	ds_read_b128 v[178:181], v251 offset:53248
	ds_read_b128 v[182:185], v251 offset:54272
	ds_read_b128 v[186:189], v251 offset:55296
	ds_read_b128 v[194:197], v251 offset:56320
	global_load_lds_dwordx4 v0, s[98:99]
	s_add_i32 m0, s20, 0x2000
	s_add_u32 s20, s22, 0x58080
	s_addc_u32 s21, s23, 0
	s_add_i32 s22, s54, s35
	global_load_lds_dwordx4 v198, s[98:99]
	s_mov_b32 m0, s22
	s_nop 0
	global_load_lds_dwordx4 v0, s[20:21]
	s_add_i32 m0, s22, 0x2000
	s_nop 0
	global_load_lds_dwordx4 v198, s[20:21]
	s_mov_b32 m0, s43
	s_nop 0
	global_load_lds_dwordx4 v190, s[100:101]
	s_mov_b32 m0, s44
	s_nop 0
	global_load_lds_dwordx4 v192, s[100:101]
	s_waitcnt vmcnt(8)
	s_waitcnt lgkmcnt(0)
	s_barrier
;     DI void operator()(const f32x4 (&acc)[2][2][4][2], const Unit& u, int wr, int wc, int fr, int fq) const {
;         const int row0 = u.pm * BM + wr * 64 + fr, col0 = u.pn * BM + wc * 64 + 8 * fq;
;         const size_t hbase = (size_t)u.pn * ((size_t)M * 256) + wc * 64 + 8 * fq;
;         u32x4 H[2][4][2];
; #pragma unroll
;         for (int ai = 0; ai < 2; ++ai)
; #pragma unroll
;             for (int m = 0; m < 4; ++m)
; #pragma unroll
;                 for (int bj = 0; bj < 2; ++bj) H[ai][m][bj] = *(const GAS u32x4*)(hi + hbase + (size_t)(row0 + ai * HALF + m * 16) * 256 + bj * 32);
;         asm volatile("" ::: "memory");
; #pragma unroll
;         for (int ai = 0; ai < 2; ++ai) {
; #pragma unroll
;             for (int m = 0; m < 4; ++m) {
;                 const int r = row0 + ai * HALF + m * 16; const size_t off = (size_t)r * DM + col0; float ss = 0.f;
; #pragma unroll
;                 for (int bj = 0; bj < 2; ++bj) {
;                     const u32x4 h = H[ai][m][bj];
;                     const f32x4 a0 = acc[ai][bj][m][0], a1 = acc[ai][bj][m][1];
;                     float v[8];
;                     v[0] = bflo(h.x) + a0[0] * scale; v[1] = bfhi(h.x) + a0[1] * scale;
;                     v[2] = bflo(h.y) + a0[2] * scale; v[3] = bfhi(h.y) + a0[3] * scale;
;                     v[4] = bflo(h.z) + a1[0] * scale; v[5] = bfhi(h.z) + a1[1] * scale;
;                     v[6] = bflo(h.w) + a1[2] * scale; v[7] = bfhi(h.w) + a1[3] * scale;
; #pragma unroll
;                     for (int e = 0; e < 8; ++e) ss += v[e] * v[e];
;                     u32x4 nh;
;                     nh.x = cvtpk(v[0], v[1]); nh.y = cvtpk(v[2], v[3]); nh.z = cvtpk(v[4], v[5]); nh.w = cvtpk(v[6], v[7]);
;                     *(GAS u32x4*)(hi + hbase + (size_t)r * 256 + bj * 32) = nh;
;                     if (out) { *(GAS f32x4*)(out + off + bj * 32) = (f32x4){v[0], v[1], v[2], v[3]}; *(GAS f32x4*)(out + off + bj * 32 + 4) = (f32x4){v[4], v[5], v[6], v[7]}; }
; template <class Epi, class Sched, int KC, bool ALIGN_EPI = false, bool SP2 = false, bool ATILED = false>
; __device__ __forceinline__ void gemm_phase(LAS unsigned char* lds, const Gemm g, const Sched& S, const Epi& E, int wave_s) {
;     ...
;             PG8_WAIT_V(8); PG8_WAIT_L(0); PG8_BAR; PG8_MMA(1, 0, At, B0); PG8_MMA(1, 1, At, B1); PG8_BAR; PG8_SCHED;
;             } else {
	s_setprio 1
	s_waitcnt lgkmcnt(0)
	v_mfma_f32_16x16x32_bf16 v[62:65], v[82:85], v[154:157], v[62:65]
	v_mfma_f32_16x16x32_bf16 v[58:61], v[106:109], v[154:157], v[58:61]
	v_mfma_f32_16x16x32_bf16 v[46:49], v[82:85], v[170:173], v[46:49]
	v_mfma_f32_16x16x32_bf16 v[42:45], v[106:109], v[170:173], v[42:45]
	v_mfma_f32_16x16x32_bf16 v[30:33], v[82:85], v[178:181], v[30:33]
	v_mfma_f32_16x16x32_bf16 v[26:29], v[106:109], v[178:181], v[26:29]
	v_mfma_f32_16x16x32_bf16 v[14:17], v[82:85], v[186:189], v[14:17]
	v_mfma_f32_16x16x32_bf16 v[10:13], v[106:109], v[186:189], v[10:13]
	v_mfma_f32_16x16x32_bf16 v[62:65], v[94:97], v[166:169], v[62:65]
	v_mfma_f32_16x16x32_bf16 v[58:61], v[114:117], v[166:169], v[58:61]
	v_mfma_f32_16x16x32_bf16 v[46:49], v[94:97], v[174:177], v[46:49]
	v_mfma_f32_16x16x32_bf16 v[42:45], v[114:117], v[174:177], v[42:45]
	v_mfma_f32_16x16x32_bf16 v[30:33], v[94:97], v[182:185], v[30:33]
	v_mfma_f32_16x16x32_bf16 v[26:29], v[114:117], v[182:185], v[26:29]
	v_mfma_f32_16x16x32_bf16 v[14:17], v[94:97], v[194:197], v[14:17]
	v_mfma_f32_16x16x32_bf16 v[10:13], v[114:117], v[194:197], v[10:13]
	s_setprio 0
	s_setprio 1
	v_mfma_f32_16x16x32_bf16 v[54:57], v[130:133], v[154:157], v[54:57]
	v_mfma_f32_16x16x32_bf16 v[50:53], v[146:149], v[154:157], v[50:53]
	v_mfma_f32_16x16x32_bf16 v[38:41], v[130:133], v[170:173], v[38:41]
	v_mfma_f32_16x16x32_bf16 v[34:37], v[146:149], v[170:173], v[34:37]
	v_mfma_f32_16x16x32_bf16 v[22:25], v[130:133], v[178:181], v[22:25]
	v_mfma_f32_16x16x32_bf16 v[18:21], v[146:149], v[178:181], v[18:21]
	v_mfma_f32_16x16x32_bf16 v[6:9], v[130:133], v[186:189], v[6:9]
	v_mfma_f32_16x16x32_bf16 v[2:5], v[146:149], v[186:189], v[2:5]
	v_mfma_f32_16x16x32_bf16 v[54:57], v[134:137], v[166:169], v[54:57]
	v_mfma_f32_16x16x32_bf16 v[50:53], v[150:153], v[166:169], v[50:53]
	v_mfma_f32_16x16x32_bf16 v[38:41], v[134:137], v[174:177], v[38:41]
	v_mfma_f32_16x16x32_bf16 v[34:37], v[150:153], v[174:177], v[34:37]
	v_mfma_f32_16x16x32_bf16 v[22:25], v[134:137], v[182:185], v[22:25]
	v_mfma_f32_16x16x32_bf16 v[18:21], v[150:153], v[182:185], v[18:21]
	v_mfma_f32_16x16x32_bf16 v[6:9], v[134:137], v[194:197], v[6:9]
	v_mfma_f32_16x16x32_bf16 v[2:5], v[150:153], v[194:197], v[2:5]
	s_setprio 0
	s_barrier
	s_add_i32 s52, s52, 2
	s_add_u32 s50, s50, 0x100
	s_addc_u32 s51, s51, 0
	s_cmpk_gt_u32 s52, 0x55
	s_mov_b64 s[20:21], s[8:9]
	s_cbranch_scc0 .LBB0_318
	v_lshl_add_u32 v206, s19, 8, v248
	s_ashr_i32 s19, s18, 31
	s_lshl_b64 s[8:9], s[18:19], 23
	v_ashrrev_i32_e32 v207, 31, v206
	v_or_b32_e32 v236, 16, v206
	v_lshl_add_u64 v[82:83], v[200:201], 0, s[8:9]
	v_lshlrev_b64 v[84:85], 9, v[206:207]
	v_ashrrev_i32_e32 v237, 31, v236
	v_or_b32_e32 v232, 32, v206
	v_lshl_add_u64 v[238:239], v[82:83], 0, v[84:85]
	v_lshlrev_b64 v[84:85], 9, v[236:237]
	v_ashrrev_i32_e32 v233, 31, v232
	v_or_b32_e32 v228, 48, v206
	v_lshl_add_u64 v[234:235], v[82:83], 0, v[84:85]
	v_lshlrev_b64 v[84:85], 9, v[232:233]
	v_ashrrev_i32_e32 v229, 31, v228
	v_add_u32_e32 v224, 0x80, v206
	v_lshl_add_u64 v[230:231], v[82:83], 0, v[84:85]
	v_lshlrev_b64 v[84:85], 9, v[228:229]
	v_ashrrev_i32_e32 v225, 31, v224
	v_add_u32_e32 v220, 0x90, v206
	global_load_dwordx4 v[194:197], v[238:239], off
	global_load_dwordx4 v[186:189], v[238:239], off offset:64
	v_lshl_add_u64 v[226:227], v[82:83], 0, v[84:85]
	v_lshlrev_b64 v[84:85], 9, v[224:225]
	v_ashrrev_i32_e32 v221, 31, v220
	v_add_u32_e32 v216, 0xa0, v206
	v_lshl_add_u64 v[222:223], v[82:83], 0, v[84:85]
	v_lshlrev_b64 v[84:85], 9, v[220:221]
	v_ashrrev_i32_e32 v217, 31, v216
	v_add_u32_e32 v210, 0xb0, v206
	v_lshl_add_u64 v[218:219], v[82:83], 0, v[84:85]
	v_lshlrev_b64 v[84:85], 9, v[216:217]
	v_ashrrev_i32_e32 v211, 31, v210
	v_lshl_add_u64 v[214:215], v[82:83], 0, v[84:85]
	v_lshlrev_b64 v[84:85], 9, v[210:211]
	v_lshl_add_u64 v[208:209], v[82:83], 0, v[84:85]
	global_load_dwordx4 v[182:185], v[234:235], off
	global_load_dwordx4 v[178:181], v[234:235], off offset:64
	global_load_dwordx4 v[174:177], v[230:231], off
	global_load_dwordx4 v[170:173], v[230:231], off offset:64
	global_load_dwordx4 v[166:169], v[226:227], off
	global_load_dwordx4 v[154:157], v[226:227], off offset:64
	global_load_dwordx4 v[150:153], v[222:223], off
	global_load_dwordx4 v[146:149], v[222:223], off offset:64
	global_load_dwordx4 v[134:137], v[218:219], off
	global_load_dwordx4 v[130:133], v[218:219], off offset:64
	global_load_dwordx4 v[114:117], v[214:215], off
	global_load_dwordx4 v[106:109], v[214:215], off offset:64
	global_load_dwordx4 v[94:97], v[208:209], off
	global_load_dwordx4 v[82:85], v[208:209], off offset:64
	v_lshl_or_b32 v212, s18, 8, v250
	v_ashrrev_i32_e32 v213, 31, v212
	v_lshlrev_b64 v[240:241], 11, v[206:207]
	v_lshl_add_u64 v[240:241], v[240:241], 0, v[212:213]
	s_andn2_b64 vcc, exec, s[14:15]
	v_lshl_add_u64 v[240:241], v[240:241], 2, s[12:13]
	s_waitcnt vmcnt(0)
	v_lshlrev_b32_e32 v252, 16, v194
	v_and_b32_e32 v253, 0xffff0000, v194
	v_lshlrev_b32_e32 v194, 16, v195
	v_and_b32_e32 v195, 0xffff0000, v195
	v_pk_fma_f32 v[164:165], v[164:165], 0.5, v[194:195] op_sel_hi:[1,0,1]
	v_lshlrev_b32_e32 v194, 16, v196
	v_and_b32_e32 v195, 0xffff0000, v196
	v_pk_fma_f32 v[158:159], v[158:159], 0.5, v[194:195] op_sel_hi:[1,0,1]
	v_lshlrev_b32_e32 v194, 16, v197
	v_and_b32_e32 v195, 0xffff0000, v197
	v_pk_fma_f32 v[162:163], v[162:163], 0.5, v[252:253] op_sel_hi:[1,0,1]
	v_pk_fma_f32 v[160:161], v[160:161], 0.5, v[194:195] op_sel_hi:[1,0,1]
	v_cvt_pk_bf16_f32 v194, v162, v163
	v_cvt_pk_bf16_f32 v195, v164, v165
	v_cvt_pk_bf16_f32 v196, v158, v159
	s_nop 0
	v_cvt_pk_bf16_f32 v197, v160, v161
	global_store_dwordx4 v[238:239], v[194:197], off
	s_nop 1
	v_cndmask_b32_e64 v194, 0, 1, s[14:15]
	v_cmp_ne_u32_e64 s[8:9], 1, v194
	s_cbranch_vccnz .LBB0_321
	global_store_dwordx4 v[240:241], v[162:165], off
	global_store_dwordx4 v[240:241], v[158:161], off offset:16

; #define PG8_STAGE(bufoff, gbase, voff) do { _Pragma("unroll") for (int _i = 0; _i < 2; ++_i) \
;         __builtin_amdgcn_global_load_lds((const unsigned*)((const char*)(gbase) + (voff)[_i]), (LAS unsigned*)(lds + (bufoff) + ldsw + _i * 8192), 16, 0, 0); } while (0)
; #define PG8_LDA(dst, b, h) do { _Pragma("unroll") for (int m = 0; m < 4; ++m) _Pragma("unroll") for (int k = 0; k < 2; ++k) dst[m][k] = *(const LAS bf16x8*)(lds + PG8_SA(b, h) + aoff + m * 2048 + k * 1024); } while (0)
; #define PG8_LDB(dst, b, h) do { _Pragma("unroll") for (int n = 0; n < 2; ++n) _Pragma("unroll") for (int k = 0; k < 2; ++k) dst[n][k] = *(const LAS bf16x8*)(lds + PG8_SB(b, h) + boff + n * 2048 + k * 1024); } while (0)
; #define PG8_MMA(ai, bj, At, Bt) do { __builtin_amdgcn_s_setprio(1); _Pragma("unroll") for (int m = 0; m < 4; ++m) _Pragma("unroll") for (int n = 0; n < 2; ++n) _Pragma("unroll") for (int k = 0; k < 2; ++k) \
;         acc[ai][bj][m][n] = __builtin_amdgcn_mfma_f32_16x16x32_bf16(Bt[n][k], At[m][k], acc[ai][bj][m][n], 0, 0, 0); __builtin_amdgcn_s_setprio(0); } while (0)
; #define PG8_WAIT_V(n) asm volatile("s_waitcnt vmcnt(" #n ")" ::: "memory")
; #define PG8_BAR __builtin_amdgcn_s_barrier()
; template <class Epi, class Sched, int KC, bool ALIGN_EPI = false, bool SP2 = false, bool ATILED = false>
; __device__ __forceinline__ void gemm_phase(LAS unsigned char* lds, const Gemm g, const Sched& S, const Epi& E, int wave_s) {
;     ...
;         for (int t = 0; t < nt; t += 2) {
;             const bool last = (t == nt - 2);
;             const char* a1 = cA + PG8_AOFF(t + 1);
;             const char* a2 = last ? nA : cA + PG8_AOFF(t + 2); const char* b2 = last ? nB : cB + (size_t)(t + 2) * kstep;
;             const char* a3 = a2 + kstep; const char* b3 = b2 + kstep;
;             if (last && has_next) S.a_ready(nxt);
;             if constexpr (SP2) {
;             PG8_LDB(B0, 0, 0); PG8_LDB(B1, 0, 1); PG8_SCHED; PG8_LDA(At, 0, 0); PG8_STAGE(PG8_SA(1, 1), a1 + hstepA, voffA);
;             PG8_WAIT_V(8); PG8_WAIT_L(0); PG8_BAR; PG8_MMA(0, 0, At, B0); PG8_MMA(0, 1, At, B1); PG8_BAR; PG8_SCHED;
;             PG8_LDA(At, 0, 1); PG8_STAGE(PG8_SB(0, 0), b2, voffB); PG8_STAGE(PG8_SB(0, 1), b2 + hstepB, voffB); PG8_STAGE(PG8_SA(0, 0), a2, voffA);
;             PG8_WAIT_V(8); PG8_WAIT_L(0); PG8_BAR; PG8_MMA(1, 0, At, B0); PG8_MMA(1, 1, At, B1); PG8_BAR; PG8_SCHED;
.LBB0_430:
	s_add_i32 s30, s66, 0xffc00000
	s_and_b32 s30, s30, 0x3800000
	s_and_b32 s31, s28, 0x100
	s_or_b32 s67, s31, s30
	s_and_b32 s34, s66, 0x7800000
	s_add_u32 s30, s28, 0x100
	s_addc_u32 s31, s29, 0
	s_and_b32 s35, s30, 0x100
	s_or_b32 s34, s34, s35
	s_add_u32 s34, s26, s34
	s_addc_u32 s35, s27, 0
	s_add_u32 s28, s63, s28
	s_addc_u32 s29, s64, s29
	s_add_i32 s70, 0, 0x10000
	s_cmp_eq_u32 s65, 28
	s_cselect_b32 s35, s19, s35
	s_cselect_b32 s34, s61, s34
	v_add_u32_e32 v139, s70, v165
	s_cselect_b32 s29, s17, s29
	s_cselect_b32 s28, s62, s28
	s_add_i32 s71, 0, 0x14000
	ds_read_b128 v[152:155], v139
	ds_read_b128 v[160:163], v139 offset:1024
	ds_read_b128 v[174:177], v139 offset:2048
	ds_read_b128 v[178:181], v139 offset:3072
	v_add_u32_e32 v139, s71, v165
	ds_read_b128 v[182:185], v139
	ds_read_b128 v[186:189], v139 offset:1024
	ds_read_b128 v[190:193], v139 offset:2048
	ds_read_b128 v[194:197], v139 offset:3072
	s_add_u32 s67, s26, s67
	s_addc_u32 s69, s27, 0
	s_add_u32 s68, s67, 0x10080
	s_addc_u32 s69, s69, 0
	s_add_i32 m0, s25, 0xc000
	ds_read_b128 v[198:201], v173
	ds_read_b128 v[202:205], v173 offset:1024
	ds_read_b128 v[206:209], v173 offset:2048
	ds_read_b128 v[210:213], v173 offset:3072
	ds_read_b128 v[214:217], v173 offset:4096
	ds_read_b128 v[218:221], v173 offset:5120
	ds_read_b128 v[222:225], v173 offset:6144
	ds_read_b128 v[226:229], v173 offset:7168
	global_load_lds_dwordx4 v136, s[68:69]
	s_add_i32 m0, s25, 0xe000
	s_nop 0
	global_load_lds_dwordx4 v132, s[68:69]
	s_waitcnt vmcnt(8)
	s_waitcnt lgkmcnt(0)
	s_barrier
	s_setprio 1
	s_waitcnt lgkmcnt(0)
	v_mfma_f32_16x16x32_bf16 v[126:129], v[152:155], v[198:201], v[126:129]
	v_mfma_f32_16x16x32_bf16 v[122:125], v[174:177], v[198:201], v[122:125]
	v_mfma_f32_16x16x32_bf16 v[114:117], v[152:155], v[206:209], v[114:117]
	v_mfma_f32_16x16x32_bf16 v[106:109], v[174:177], v[206:209], v[106:109]
	v_mfma_f32_16x16x32_bf16 v[98:101], v[152:155], v[214:217], v[98:101]
	v_mfma_f32_16x16x32_bf16 v[90:93], v[174:177], v[214:217], v[90:93]
	v_mfma_f32_16x16x32_bf16 v[82:85], v[152:155], v[222:225], v[82:85]
	v_mfma_f32_16x16x32_bf16 v[74:77], v[174:177], v[222:225], v[74:77]
	v_mfma_f32_16x16x32_bf16 v[126:129], v[160:163], v[202:205], v[126:129]
	v_mfma_f32_16x16x32_bf16 v[122:125], v[178:181], v[202:205], v[122:125]
	v_mfma_f32_16x16x32_bf16 v[114:117], v[160:163], v[210:213], v[114:117]
	v_mfma_f32_16x16x32_bf16 v[106:109], v[178:181], v[210:213], v[106:109]
	v_mfma_f32_16x16x32_bf16 v[98:101], v[160:163], v[218:221], v[98:101]
	v_mfma_f32_16x16x32_bf16 v[90:93], v[178:181], v[218:221], v[90:93]
	v_mfma_f32_16x16x32_bf16 v[82:85], v[160:163], v[226:229], v[82:85]
	v_mfma_f32_16x16x32_bf16 v[74:77], v[178:181], v[226:229], v[74:77]
	s_setprio 0
	s_setprio 1
	v_mfma_f32_16x16x32_bf16 v[118:121], v[182:185], v[198:201], v[118:121]
	v_mfma_f32_16x16x32_bf16 v[110:113], v[190:193], v[198:201], v[110:113]
	v_mfma_f32_16x16x32_bf16 v[102:105], v[182:185], v[206:209], v[102:105]
	v_mfma_f32_16x16x32_bf16 v[94:97], v[190:193], v[206:209], v[94:97]
	v_mfma_f32_16x16x32_bf16 v[86:89], v[182:185], v[214:217], v[86:89]
	v_mfma_f32_16x16x32_bf16 v[78:81], v[190:193], v[214:217], v[78:81]
	v_mfma_f32_16x16x32_bf16 v[70:73], v[182:185], v[222:225], v[70:73]
	v_mfma_f32_16x16x32_bf16 v[66:69], v[190:193], v[222:225], v[66:69]
	v_mfma_f32_16x16x32_bf16 v[118:121], v[186:189], v[202:205], v[118:121]
	v_mfma_f32_16x16x32_bf16 v[110:113], v[194:197], v[202:205], v[110:113]
	v_mfma_f32_16x16x32_bf16 v[102:105], v[186:189], v[210:213], v[102:105]
	v_mfma_f32_16x16x32_bf16 v[94:97], v[194:197], v[210:213], v[94:97]
	v_mfma_f32_16x16x32_bf16 v[86:89], v[186:189], v[218:221], v[86:89]
	v_mfma_f32_16x16x32_bf16 v[78:81], v[194:197], v[218:221], v[78:81]
	v_mfma_f32_16x16x32_bf16 v[70:73], v[186:189], v[226:229], v[70:73]
	v_mfma_f32_16x16x32_bf16 v[66:69], v[194:197], v[226:229], v[66:69]
	s_setprio 0
	s_barrier
	s_add_u32 s100, s34, 0x80
	s_addc_u32 s101, s35, 0
	s_add_i32 s67, s70, s41
	s_mov_b32 m0, s67
	ds_read_b128 v[198:201], v173 offset:16384
	ds_read_b128 v[202:205], v173 offset:17408
	ds_read_b128 v[206:209], v173 offset:18432
	ds_read_b128 v[210:213], v173 offset:19456
	ds_read_b128 v[214:217], v173 offset:20480
	ds_read_b128 v[218:221], v173 offset:21504
	ds_read_b128 v[222:225], v173 offset:22528
	ds_read_b128 v[226:229], v173 offset:23552
	global_load_lds_dwordx4 v134, s[28:29]
	s_add_i32 m0, s67, 0x2000
	s_add_u32 s68, s28, 0x80000
	s_addc_u32 s69, s29, 0
	s_add_i32 s67, s71, s41
	global_load_lds_dwordx4 v130, s[28:29]
	s_mov_b32 m0, s67
	s_nop 0
	global_load_lds_dwordx4 v134, s[68:69]
	s_add_i32 m0, s67, 0x2000
	s_nop 0
	global_load_lds_dwordx4 v130, s[68:69]
	s_mov_b32 m0, s25
	s_nop 0
	global_load_lds_dwordx4 v136, s[34:35]
	s_mov_b32 m0, s52
	s_nop 0
	global_load_lds_dwordx4 v132, s[34:35]
	s_waitcnt vmcnt(8)
	s_waitcnt lgkmcnt(0)
	s_barrier
; #define PG8_STAGE(bufoff, gbase, voff) do { _Pragma("unroll") for (int _i = 0; _i < 2; ++_i) \
;         __builtin_amdgcn_global_load_lds((const unsigned*)((const char*)(gbase) + (voff)[_i]), (LAS unsigned*)(lds + (bufoff) + ldsw + _i * 8192), 16, 0, 0); } while (0)
; #define PG8_LDA(dst, b, h) do { _Pragma("unroll") for (int m = 0; m < 4; ++m) _Pragma("unroll") for (int k = 0; k < 2; ++k) dst[m][k] = *(const LAS bf16x8*)(lds + PG8_SA(b, h) + aoff + m * 2048 + k * 1024); } while (0)
; #define PG8_LDB(dst, b, h) do { _Pragma("unroll") for (int n = 0; n < 2; ++n) _Pragma("unroll") for (int k = 0; k < 2; ++k) dst[n][k] = *(const LAS bf16x8*)(lds + PG8_SB(b, h) + boff + n * 2048 + k * 1024); } while (0)
; #define PG8_MMA(ai, bj, At, Bt) do { __builtin_amdgcn_s_setprio(1); _Pragma("unroll") for (int m = 0; m < 4; ++m) _Pragma("unroll") for (int n = 0; n < 2; ++n) _Pragma("unroll") for (int k = 0; k < 2; ++k) \
;         acc[ai][bj][m][n] = __builtin_amdgcn_mfma_f32_16x16x32_bf16(Bt[n][k], At[m][k], acc[ai][bj][m][n], 0, 0, 0); __builtin_amdgcn_s_setprio(0); } while (0)
; #define PG8_WAIT_V(n) asm volatile("s_waitcnt vmcnt(" #n ")" ::: "memory")
; #define PG8_WAIT_L(n) asm volatile("s_waitcnt lgkmcnt(" #n ")" ::: "memory")
; #define PG8_BAR __builtin_amdgcn_s_barrier()
; #define PG8_SCHED __builtin_amdgcn_sched_barrier(0)
; template <class Epi, class Sched, int KC, bool ALIGN_EPI = false, bool SP2 = false, bool ATILED = false>
; __device__ __forceinline__ void gemm_phase(LAS unsigned char* lds, const Gemm g, const Sched& S, const Epi& E, int wave_s) {
;     ...
;             PG8_WAIT_V(8); PG8_WAIT_L(0); PG8_BAR; PG8_MMA(1, 0, At, B0); PG8_MMA(1, 1, At, B1); PG8_BAR; PG8_SCHED;
;             PG8_LDB(B0, 1, 0); PG8_LDB(B1, 1, 1); PG8_SCHED; PG8_LDA(At, 1, 0); PG8_STAGE(PG8_SA(0, 1), a2 + hstepA, voffA);
;             PG8_WAIT_V(8); PG8_WAIT_L(0); PG8_BAR; PG8_MMA(0, 0, At, B0); PG8_MMA(0, 1, At, B1); PG8_BAR; PG8_SCHED;
	s_setprio 1
	s_waitcnt lgkmcnt(0)
	v_mfma_f32_16x16x32_bf16 v[62:65], v[152:155], v[198:201], v[62:65]
	v_mfma_f32_16x16x32_bf16 v[58:61], v[174:177], v[198:201], v[58:61]
	v_mfma_f32_16x16x32_bf16 v[50:53], v[152:155], v[206:209], v[50:53]
	v_mfma_f32_16x16x32_bf16 v[42:45], v[174:177], v[206:209], v[42:45]
	v_mfma_f32_16x16x32_bf16 v[34:37], v[152:155], v[214:217], v[34:37]
	v_mfma_f32_16x16x32_bf16 v[26:29], v[174:177], v[214:217], v[26:29]
	v_mfma_f32_16x16x32_bf16 v[18:21], v[152:155], v[222:225], v[18:21]
	v_mfma_f32_16x16x32_bf16 v[10:13], v[174:177], v[222:225], v[10:13]
	v_mfma_f32_16x16x32_bf16 v[62:65], v[160:163], v[202:205], v[62:65]
	v_mfma_f32_16x16x32_bf16 v[58:61], v[178:181], v[202:205], v[58:61]
	v_mfma_f32_16x16x32_bf16 v[50:53], v[160:163], v[210:213], v[50:53]
	v_mfma_f32_16x16x32_bf16 v[42:45], v[178:181], v[210:213], v[42:45]
	v_mfma_f32_16x16x32_bf16 v[34:37], v[160:163], v[218:221], v[34:37]
	v_mfma_f32_16x16x32_bf16 v[26:29], v[178:181], v[218:221], v[26:29]
	v_mfma_f32_16x16x32_bf16 v[18:21], v[160:163], v[226:229], v[18:21]
	v_mfma_f32_16x16x32_bf16 v[10:13], v[178:181], v[226:229], v[10:13]
	s_setprio 0
	s_setprio 1
	v_mfma_f32_16x16x32_bf16 v[54:57], v[182:185], v[198:201], v[54:57]
	v_mfma_f32_16x16x32_bf16 v[46:49], v[190:193], v[198:201], v[46:49]
	v_mfma_f32_16x16x32_bf16 v[38:41], v[182:185], v[206:209], v[38:41]
	v_mfma_f32_16x16x32_bf16 v[30:33], v[190:193], v[206:209], v[30:33]
	v_mfma_f32_16x16x32_bf16 v[22:25], v[182:185], v[214:217], v[22:25]
	v_mfma_f32_16x16x32_bf16 v[14:17], v[190:193], v[214:217], v[14:17]
	v_mfma_f32_16x16x32_bf16 v[6:9], v[182:185], v[222:225], v[6:9]
	v_mfma_f32_16x16x32_bf16 v[2:5], v[190:193], v[222:225], v[2:5]
	v_mfma_f32_16x16x32_bf16 v[54:57], v[186:189], v[202:205], v[54:57]
	v_mfma_f32_16x16x32_bf16 v[46:49], v[194:197], v[202:205], v[46:49]
	v_mfma_f32_16x16x32_bf16 v[38:41], v[186:189], v[210:213], v[38:41]
	v_mfma_f32_16x16x32_bf16 v[30:33], v[194:197], v[210:213], v[30:33]
	v_mfma_f32_16x16x32_bf16 v[22:25], v[186:189], v[218:221], v[22:25]
	v_mfma_f32_16x16x32_bf16 v[14:17], v[194:197], v[218:221], v[14:17]
	v_mfma_f32_16x16x32_bf16 v[6:9], v[186:189], v[226:229], v[6:9]
	v_mfma_f32_16x16x32_bf16 v[2:5], v[194:197], v[226:229], v[2:5]
	s_setprio 0
	s_barrier
	s_add_i32 s67, 0, 0x18000
	v_add_u32_e32 v139, s67, v165
	s_add_i32 s68, 0, 0x1c000
	ds_read_b128 v[152:155], v139
	ds_read_b128 v[160:163], v139 offset:1024
	ds_read_b128 v[174:177], v139 offset:2048
	ds_read_b128 v[178:181], v139 offset:3072
	v_add_u32_e32 v139, s68, v165
	ds_read_b128 v[182:185], v139
	ds_read_b128 v[186:189], v139 offset:1024
	ds_read_b128 v[190:193], v139 offset:2048
	ds_read_b128 v[194:197], v139 offset:3072
	s_add_u32 s34, s34, 0x10000
	s_addc_u32 s35, s35, 0
	s_mov_b32 m0, s53
	ds_read_b128 v[198:201], v173 offset:32768
	ds_read_b128 v[202:205], v173 offset:33792
	ds_read_b128 v[206:209], v173 offset:34816
	ds_read_b128 v[210:213], v173 offset:35840
	ds_read_b128 v[214:217], v173 offset:36864
	ds_read_b128 v[218:221], v173 offset:37888
	ds_read_b128 v[222:225], v173 offset:38912
	ds_read_b128 v[226:229], v173 offset:39936
	global_load_lds_dwordx4 v136, s[34:35]
	s_mov_b32 m0, s54
	s_nop 0
	global_load_lds_dwordx4 v132, s[34:35]
	s_waitcnt vmcnt(8)
	s_waitcnt lgkmcnt(0)
	s_barrier
	s_setprio 1
	s_waitcnt lgkmcnt(0)
	v_mfma_f32_16x16x32_bf16 v[126:129], v[152:155], v[198:201], v[126:129]
	v_mfma_f32_16x16x32_bf16 v[122:125], v[174:177], v[198:201], v[122:125]
	v_mfma_f32_16x16x32_bf16 v[114:117], v[152:155], v[206:209], v[114:117]
	v_mfma_f32_16x16x32_bf16 v[106:109], v[174:177], v[206:209], v[106:109]
	v_mfma_f32_16x16x32_bf16 v[98:101], v[152:155], v[214:217], v[98:101]
	v_mfma_f32_16x16x32_bf16 v[90:93], v[174:177], v[214:217], v[90:93]
	v_mfma_f32_16x16x32_bf16 v[82:85], v[152:155], v[222:225], v[82:85]
	v_mfma_f32_16x16x32_bf16 v[74:77], v[174:177], v[222:225], v[74:77]
	v_mfma_f32_16x16x32_bf16 v[126:129], v[160:163], v[202:205], v[126:129]
	v_mfma_f32_16x16x32_bf16 v[122:125], v[178:181], v[202:205], v[122:125]
	v_mfma_f32_16x16x32_bf16 v[114:117], v[160:163], v[210:213], v[114:117]
	v_mfma_f32_16x16x32_bf16 v[106:109], v[178:181], v[210:213], v[106:109]
	v_mfma_f32_16x16x32_bf16 v[98:101], v[160:163], v[218:221], v[98:101]
	v_mfma_f32_16x16x32_bf16 v[90:93], v[178:181], v[218:221], v[90:93]
	v_mfma_f32_16x16x32_bf16 v[82:85], v[160:163], v[226:229], v[82:85]
	v_mfma_f32_16x16x32_bf16 v[74:77], v[178:181], v[226:229], v[74:77]
	s_setprio 0
	s_setprio 1
	v_mfma_f32_16x16x32_bf16 v[118:121], v[182:185], v[198:201], v[118:121]
	v_mfma_f32_16x16x32_bf16 v[110:113], v[190:193], v[198:201], v[110:113]
	v_mfma_f32_16x16x32_bf16 v[102:105], v[182:185], v[206:209], v[102:105]
	v_mfma_f32_16x16x32_bf16 v[94:97], v[190:193], v[206:209], v[94:97]
	v_mfma_f32_16x16x32_bf16 v[86:89], v[182:185], v[214:217], v[86:89]
	v_mfma_f32_16x16x32_bf16 v[78:81], v[190:193], v[214:217], v[78:81]
	v_mfma_f32_16x16x32_bf16 v[70:73], v[182:185], v[222:225], v[70:73]
	v_mfma_f32_16x16x32_bf16 v[66:69], v[190:193], v[222:225], v[66:69]
	v_mfma_f32_16x16x32_bf16 v[118:121], v[186:189], v[202:205], v[118:121]
	v_mfma_f32_16x16x32_bf16 v[110:113], v[194:197], v[202:205], v[110:113]
	v_mfma_f32_16x16x32_bf16 v[102:105], v[186:189], v[210:213], v[102:105]
	v_mfma_f32_16x16x32_bf16 v[94:97], v[194:197], v[210:213], v[94:97]
	v_mfma_f32_16x16x32_bf16 v[86:89], v[186:189], v[218:221], v[86:89]
	v_mfma_f32_16x16x32_bf16 v[78:81], v[194:197], v[218:221], v[78:81]
	v_mfma_f32_16x16x32_bf16 v[70:73], v[186:189], v[226:229], v[70:73]
	v_mfma_f32_16x16x32_bf16 v[66:69], v[194:197], v[226:229], v[66:69]
	s_setprio 0
	s_barrier
; #define PG8_STAGE(bufoff, gbase, voff) do { _Pragma("unroll") for (int _i = 0; _i < 2; ++_i) \
;         __builtin_amdgcn_global_load_lds((const unsigned*)((const char*)(gbase) + (voff)[_i]), (LAS unsigned*)(lds + (bufoff) + ldsw + _i * 8192), 16, 0, 0); } while (0)
; #define PG8_LDA(dst, b, h) do { _Pragma("unroll") for (int m = 0; m < 4; ++m) _Pragma("unroll") for (int k = 0; k < 2; ++k) dst[m][k] = *(const LAS bf16x8*)(lds + PG8_SA(b, h) + aoff + m * 2048 + k * 1024); } while (0)
; #define PG8_BAR __builtin_amdgcn_s_barrier()
; template <class Epi, class Sched, int KC, bool ALIGN_EPI = false, bool SP2 = false, bool ATILED = false>
; __device__ __forceinline__ void gemm_phase(LAS unsigned char* lds, const Gemm g, const Sched& S, const Epi& E, int wave_s) {
;     ...
;             PG8_LDA(At, 1, 1); PG8_STAGE(PG8_SB(1, 0), b3, voffB); PG8_STAGE(PG8_SB(1, 1), b3 + hstepB, voffB); PG8_STAGE(PG8_SA(1, 0), a3, voffA);
;             PG8_WAIT_V(8); PG8_WAIT_L(0); PG8_BAR; PG8_MMA(1, 0, At, B0); PG8_MMA(1, 1, At, B1); PG8_BAR; PG8_SCHED;
;             } else {
;             PG8_LDB(B0, 0, 0); PG8_SCHED; PG8_LDA(At, 0, 0); PG8_STAGE(PG8_SA(1, 1), a1 + hstepA, voffA);
;             PG8_WAIT_L(8); PG8_BAR; PG8_WAIT_L(0); PG8_MMA(0, 0, At, B0); PG8_BAR; PG8_SCHED;
;             PG8_LDB(B1, 0, 1); PG8_STAGE(PG8_SB(0, 0), b2, voffB);
;             PG8_BAR; PG8_WAIT_L(0); PG8_MMA(0, 1, At, B1); PG8_BAR;
;             PG8_LDA(At, 0, 1); PG8_STAGE(PG8_SA(0, 0), a2, voffA);
;             PG8_BAR; PG8_WAIT_L(0); PG8_MMA(1, 0, At, B0); PG8_BAR; PG8_SCHED;
;             PG8_STAGE(PG8_SB(0, 1), b2 + hstepB, voffB);
;             PG8_WAIT_V(6); PG8_BAR; PG8_MMA(1, 1, At, B1); PG8_BAR;
;             PG8_LDB(B0, 1, 0); PG8_SCHED; PG8_LDA(At, 1, 0); PG8_STAGE(PG8_SA(0, 1), a2 + hstepA, voffA);
;             PG8_WAIT_L(8); PG8_BAR; PG8_WAIT_L(0); PG8_MMA(0, 0, At, B0); PG8_BAR; PG8_SCHED;
;             PG8_LDB(B1, 1, 1); PG8_STAGE(PG8_SB(1, 0), b3, voffB);
;             PG8_BAR; PG8_WAIT_L(0); PG8_MMA(0, 1, At, B1); PG8_BAR;
;             PG8_LDA(At, 1, 1); PG8_STAGE(PG8_SA(1, 0), a3, voffA);
;             PG8_BAR; PG8_WAIT_L(0); PG8_MMA(1, 0, At, B0); PG8_BAR; PG8_SCHED;
;             PG8_STAGE(PG8_SB(1, 1), b3 + hstepB, voffB);
;             PG8_WAIT_V(6); PG8_BAR; PG8_MMA(1, 1, At, B1); PG8_BAR;
;             }
;         }
;         if constexpr (ALIGN_EPI) { if (wr == 0) PG8_BAR; }
	s_add_u32 s98, s28, 0x80
	s_addc_u32 s99, s29, 0
	s_add_i32 s34, s67, s41
	s_mov_b32 m0, s34
	ds_read_b128 v[198:201], v173 offset:49152
	ds_read_b128 v[202:205], v173 offset:50176
	ds_read_b128 v[206:209], v173 offset:51200
	ds_read_b128 v[210:213], v173 offset:52224
	ds_read_b128 v[214:217], v173 offset:53248
	ds_read_b128 v[218:221], v173 offset:54272
	ds_read_b128 v[222:225], v173 offset:55296
	ds_read_b128 v[226:229], v173 offset:56320
	global_load_lds_dwordx4 v134, s[98:99]
	s_add_i32 m0, s34, 0x2000
	s_add_u32 s28, s28, 0x80080
	s_addc_u32 s29, s29, 0
	s_add_i32 s34, s68, s41
	global_load_lds_dwordx4 v130, s[98:99]
	s_mov_b32 m0, s34
	s_nop 0
	global_load_lds_dwordx4 v134, s[28:29]
	s_add_i32 m0, s34, 0x2000
	s_nop 0
	global_load_lds_dwordx4 v130, s[28:29]
	s_mov_b32 m0, s55
	s_nop 0
	global_load_lds_dwordx4 v136, s[100:101]
	s_mov_b32 m0, s56
	s_nop 0
	global_load_lds_dwordx4 v132, s[100:101]
	s_waitcnt vmcnt(8)
	s_waitcnt lgkmcnt(0)
	s_barrier
	s_setprio 1
	s_waitcnt lgkmcnt(0)
	v_mfma_f32_16x16x32_bf16 v[62:65], v[152:155], v[198:201], v[62:65]
	v_mfma_f32_16x16x32_bf16 v[58:61], v[174:177], v[198:201], v[58:61]
	v_mfma_f32_16x16x32_bf16 v[50:53], v[152:155], v[206:209], v[50:53]
	v_mfma_f32_16x16x32_bf16 v[42:45], v[174:177], v[206:209], v[42:45]
	v_mfma_f32_16x16x32_bf16 v[34:37], v[152:155], v[214:217], v[34:37]
	v_mfma_f32_16x16x32_bf16 v[26:29], v[174:177], v[214:217], v[26:29]
	v_mfma_f32_16x16x32_bf16 v[18:21], v[152:155], v[222:225], v[18:21]
	v_mfma_f32_16x16x32_bf16 v[10:13], v[174:177], v[222:225], v[10:13]
	v_mfma_f32_16x16x32_bf16 v[62:65], v[160:163], v[202:205], v[62:65]
	v_mfma_f32_16x16x32_bf16 v[58:61], v[178:181], v[202:205], v[58:61]
	v_mfma_f32_16x16x32_bf16 v[50:53], v[160:163], v[210:213], v[50:53]
	v_mfma_f32_16x16x32_bf16 v[42:45], v[178:181], v[210:213], v[42:45]
	v_mfma_f32_16x16x32_bf16 v[34:37], v[160:163], v[218:221], v[34:37]
	v_mfma_f32_16x16x32_bf16 v[26:29], v[178:181], v[218:221], v[26:29]
	v_mfma_f32_16x16x32_bf16 v[18:21], v[160:163], v[226:229], v[18:21]
	v_mfma_f32_16x16x32_bf16 v[10:13], v[178:181], v[226:229], v[10:13]
	s_setprio 0
	s_setprio 1
	v_mfma_f32_16x16x32_bf16 v[54:57], v[182:185], v[198:201], v[54:57]
	v_mfma_f32_16x16x32_bf16 v[46:49], v[190:193], v[198:201], v[46:49]
	v_mfma_f32_16x16x32_bf16 v[38:41], v[182:185], v[206:209], v[38:41]
	v_mfma_f32_16x16x32_bf16 v[30:33], v[190:193], v[206:209], v[30:33]
	v_mfma_f32_16x16x32_bf16 v[22:25], v[182:185], v[214:217], v[22:25]
	v_mfma_f32_16x16x32_bf16 v[14:17], v[190:193], v[214:217], v[14:17]
	v_mfma_f32_16x16x32_bf16 v[6:9], v[182:185], v[222:225], v[6:9]
	v_mfma_f32_16x16x32_bf16 v[2:5], v[190:193], v[222:225], v[2:5]
	v_mfma_f32_16x16x32_bf16 v[54:57], v[186:189], v[202:205], v[54:57]
	v_mfma_f32_16x16x32_bf16 v[46:49], v[194:197], v[202:205], v[46:49]
	v_mfma_f32_16x16x32_bf16 v[38:41], v[186:189], v[210:213], v[38:41]
	v_mfma_f32_16x16x32_bf16 v[30:33], v[194:197], v[210:213], v[30:33]
	v_mfma_f32_16x16x32_bf16 v[22:25], v[186:189], v[218:221], v[22:25]
	v_mfma_f32_16x16x32_bf16 v[14:17], v[194:197], v[218:221], v[14:17]
	v_mfma_f32_16x16x32_bf16 v[6:9], v[186:189], v[226:229], v[6:9]
	v_mfma_f32_16x16x32_bf16 v[2:5], v[194:197], v[226:229], v[2:5]
	s_setprio 0
	s_barrier
	s_add_i32 s65, s65, 2
	s_add_i32 s66, s66, 0x400000
	s_cmp_gt_u32 s65, 29
	s_mov_b64 s[28:29], s[30:31]
	s_cbranch_scc0 .LBB0_430
	s_and_b64 vcc, exec, s[14:15]
	s_cbranch_vccz .LBB0_433
	s_barrier

; #define PG8_STAGE(bufoff, gbase, voff) do { _Pragma("unroll") for (int _i = 0; _i < 2; ++_i) \
;         __builtin_amdgcn_global_load_lds((const unsigned*)((const char*)(gbase) + (voff)[_i]), (LAS unsigned*)(lds + (bufoff) + ldsw + _i * 8192), 16, 0, 0); } while (0)
; #define PG8_LDA(dst, b, h) do { _Pragma("unroll") for (int m = 0; m < 4; ++m) _Pragma("unroll") for (int k = 0; k < 2; ++k) dst[m][k] = *(const LAS bf16x8*)(lds + PG8_SA(b, h) + aoff + m * 2048 + k * 1024); } while (0)
; #define PG8_LDB(dst, b, h) do { _Pragma("unroll") for (int n = 0; n < 2; ++n) _Pragma("unroll") for (int k = 0; k < 2; ++k) dst[n][k] = *(const LAS bf16x8*)(lds + PG8_SB(b, h) + boff + n * 2048 + k * 1024); } while (0)
; #define PG8_MMA(ai, bj, At, Bt) do { __builtin_amdgcn_s_setprio(1); _Pragma("unroll") for (int m = 0; m < 4; ++m) _Pragma("unroll") for (int n = 0; n < 2; ++n) _Pragma("unroll") for (int k = 0; k < 2; ++k) \
;         acc[ai][bj][m][n] = __builtin_amdgcn_mfma_f32_16x16x32_bf16(Bt[n][k], At[m][k], acc[ai][bj][m][n], 0, 0, 0); __builtin_amdgcn_s_setprio(0); } while (0)
; #define PG8_WAIT_V(n) asm volatile("s_waitcnt vmcnt(" #n ")" ::: "memory")
; #define PG8_BAR __builtin_amdgcn_s_barrier()
; template <class Epi, class Sched, int KC, bool ALIGN_EPI = false, bool SP2 = false, bool ATILED = false>
; __device__ __forceinline__ void gemm_phase(LAS unsigned char* lds, const Gemm g, const Sched& S, const Epi& E, int wave_s) {
;     ...
;         for (int t = 0; t < nt; t += 2) {
;             const bool last = (t == nt - 2);
;             const char* a1 = cA + PG8_AOFF(t + 1);
;             const char* a2 = last ? nA : cA + PG8_AOFF(t + 2); const char* b2 = last ? nB : cB + (size_t)(t + 2) * kstep;
;             const char* a3 = a2 + kstep; const char* b3 = b2 + kstep;
;             if (last && has_next) S.a_ready(nxt);
;             if constexpr (SP2) {
;             PG8_LDB(B0, 0, 0); PG8_LDB(B1, 0, 1); PG8_SCHED; PG8_LDA(At, 0, 0); PG8_STAGE(PG8_SA(1, 1), a1 + hstepA, voffA);
;             PG8_WAIT_V(8); PG8_WAIT_L(0); PG8_BAR; PG8_MMA(0, 0, At, B0); PG8_MMA(0, 1, At, B1); PG8_BAR; PG8_SCHED;
;             PG8_LDA(At, 0, 1); PG8_STAGE(PG8_SB(0, 0), b2, voffB); PG8_STAGE(PG8_SB(0, 1), b2 + hstepB, voffB); PG8_STAGE(PG8_SA(0, 0), a2, voffA);
;             PG8_WAIT_V(8); PG8_WAIT_L(0); PG8_BAR; PG8_MMA(1, 0, At, B0); PG8_MMA(1, 1, At, B1); PG8_BAR; PG8_SCHED;
.LBB0_1021:
	s_add_u32 s20, s18, 0xfff80080
	s_addc_u32 s21, s19, -1
	s_add_i32 s49, 0, 0x10000
	s_cmp_eq_u32 s48, 28
	s_cselect_b32 s23, s9, s21
	s_cselect_b32 s22, s15, s20
	s_cselect_b32 s21, s3, s47
	s_cselect_b32 s20, s17, s46
	s_add_i32 s52, 0, 0x14000
	v_add_u32_e32 v142, s49, v229
	v_add_u32_e32 v158, s52, v229
	ds_read_b128 v[130:133], v142
	ds_read_b128 v[134:137], v142 offset:1024
	ds_read_b128 v[138:141], v142 offset:2048
	ds_read_b128 v[142:145], v142 offset:3072
	ds_read_b128 v[146:149], v158
	ds_read_b128 v[150:153], v158 offset:1024
	ds_read_b128 v[154:157], v158 offset:2048
	ds_read_b128 v[158:161], v158 offset:3072
	s_add_i32 m0, s34, 0xc000
	ds_read_b128 v[162:165], v230
	ds_read_b128 v[166:169], v230 offset:1024
	ds_read_b128 v[170:173], v230 offset:2048
	ds_read_b128 v[174:177], v230 offset:3072
	ds_read_b128 v[178:181], v230 offset:4096
	ds_read_b128 v[182:185], v230 offset:5120
	ds_read_b128 v[186:189], v230 offset:6144
	ds_read_b128 v[190:193], v230 offset:7168
	global_load_lds_dwordx4 v208, s[18:19]
	s_add_i32 m0, s34, 0xe000
	s_nop 0
	global_load_lds_dwordx4 v206, s[18:19]
	s_waitcnt vmcnt(8)
	s_waitcnt lgkmcnt(0)
	s_barrier
	s_setprio 1
	s_waitcnt lgkmcnt(0)
	v_mfma_f32_16x16x32_bf16 v[126:129], v[130:133], v[162:165], v[126:129]
	v_mfma_f32_16x16x32_bf16 v[122:125], v[138:141], v[162:165], v[122:125]
	v_mfma_f32_16x16x32_bf16 v[110:113], v[130:133], v[170:173], v[110:113]
	v_mfma_f32_16x16x32_bf16 v[106:109], v[138:141], v[170:173], v[106:109]
	v_mfma_f32_16x16x32_bf16 v[94:97], v[130:133], v[178:181], v[94:97]
	v_mfma_f32_16x16x32_bf16 v[90:93], v[138:141], v[178:181], v[90:93]
	v_mfma_f32_16x16x32_bf16 v[78:81], v[130:133], v[186:189], v[78:81]
	v_mfma_f32_16x16x32_bf16 v[74:77], v[138:141], v[186:189], v[74:77]
	v_mfma_f32_16x16x32_bf16 v[126:129], v[134:137], v[166:169], v[126:129]
	v_mfma_f32_16x16x32_bf16 v[122:125], v[142:145], v[166:169], v[122:125]
	v_mfma_f32_16x16x32_bf16 v[110:113], v[134:137], v[174:177], v[110:113]
	v_mfma_f32_16x16x32_bf16 v[106:109], v[142:145], v[174:177], v[106:109]
	v_mfma_f32_16x16x32_bf16 v[94:97], v[134:137], v[182:185], v[94:97]
	v_mfma_f32_16x16x32_bf16 v[90:93], v[142:145], v[182:185], v[90:93]
	v_mfma_f32_16x16x32_bf16 v[78:81], v[134:137], v[190:193], v[78:81]
	v_mfma_f32_16x16x32_bf16 v[74:77], v[142:145], v[190:193], v[74:77]
	s_setprio 0
	s_setprio 1
	v_mfma_f32_16x16x32_bf16 v[118:121], v[146:149], v[162:165], v[118:121]
	v_mfma_f32_16x16x32_bf16 v[114:117], v[154:157], v[162:165], v[114:117]
	v_mfma_f32_16x16x32_bf16 v[102:105], v[146:149], v[170:173], v[102:105]
	v_mfma_f32_16x16x32_bf16 v[98:101], v[154:157], v[170:173], v[98:101]
	v_mfma_f32_16x16x32_bf16 v[86:89], v[146:149], v[178:181], v[86:89]
	v_mfma_f32_16x16x32_bf16 v[82:85], v[154:157], v[178:181], v[82:85]
	v_mfma_f32_16x16x32_bf16 v[70:73], v[146:149], v[186:189], v[70:73]
	v_mfma_f32_16x16x32_bf16 v[66:69], v[154:157], v[186:189], v[66:69]
	v_mfma_f32_16x16x32_bf16 v[118:121], v[150:153], v[166:169], v[118:121]
	v_mfma_f32_16x16x32_bf16 v[114:117], v[158:161], v[166:169], v[114:117]
	v_mfma_f32_16x16x32_bf16 v[102:105], v[150:153], v[174:177], v[102:105]
	v_mfma_f32_16x16x32_bf16 v[98:101], v[158:161], v[174:177], v[98:101]
	v_mfma_f32_16x16x32_bf16 v[86:89], v[150:153], v[182:185], v[86:89]
	v_mfma_f32_16x16x32_bf16 v[82:85], v[158:161], v[182:185], v[82:85]
	v_mfma_f32_16x16x32_bf16 v[70:73], v[150:153], v[190:193], v[70:73]
	v_mfma_f32_16x16x32_bf16 v[66:69], v[158:161], v[190:193], v[66:69]
	s_setprio 0
	s_barrier
	s_add_u32 s100, s22, 0x80
	s_addc_u32 s101, s23, 0
	s_add_i32 s49, s49, s31
	s_mov_b32 m0, s49
	ds_read_b128 v[162:165], v230 offset:16384
	ds_read_b128 v[166:169], v230 offset:17408
	ds_read_b128 v[170:173], v230 offset:18432
	ds_read_b128 v[174:177], v230 offset:19456
	ds_read_b128 v[178:181], v230 offset:20480
	ds_read_b128 v[182:185], v230 offset:21504
	ds_read_b128 v[186:189], v230 offset:22528
	ds_read_b128 v[190:193], v230 offset:23552
	global_load_lds_dwordx4 v0, s[20:21]
	s_add_i32 m0, s49, 0x2000
	s_add_u32 s50, s20, 0x20000
	s_addc_u32 s51, s21, 0
	s_add_i32 s49, s52, s31
	global_load_lds_dwordx4 v202, s[20:21]
	s_mov_b32 m0, s49
	s_nop 0
	global_load_lds_dwordx4 v0, s[50:51]
	s_add_i32 m0, s49, 0x2000
	s_nop 0
	global_load_lds_dwordx4 v202, s[50:51]
	s_mov_b32 m0, s34
	s_nop 0
	global_load_lds_dwordx4 v198, s[22:23]
	s_mov_b32 m0, s35
	s_nop 0
	global_load_lds_dwordx4 v200, s[22:23]
	s_waitcnt vmcnt(8)
	s_waitcnt lgkmcnt(0)
	s_barrier
	s_setprio 1
	s_waitcnt lgkmcnt(0)
	v_mfma_f32_16x16x32_bf16 v[62:65], v[130:133], v[162:165], v[62:65]
	v_mfma_f32_16x16x32_bf16 v[58:61], v[138:141], v[162:165], v[58:61]
	v_mfma_f32_16x16x32_bf16 v[46:49], v[130:133], v[170:173], v[46:49]
	v_mfma_f32_16x16x32_bf16 v[42:45], v[138:141], v[170:173], v[42:45]
	v_mfma_f32_16x16x32_bf16 v[30:33], v[130:133], v[178:181], v[30:33]
	v_mfma_f32_16x16x32_bf16 v[26:29], v[138:141], v[178:181], v[26:29]
	v_mfma_f32_16x16x32_bf16 v[14:17], v[130:133], v[186:189], v[14:17]
	v_mfma_f32_16x16x32_bf16 v[10:13], v[138:141], v[186:189], v[10:13]
	v_mfma_f32_16x16x32_bf16 v[62:65], v[134:137], v[166:169], v[62:65]
	v_mfma_f32_16x16x32_bf16 v[58:61], v[142:145], v[166:169], v[58:61]
	v_mfma_f32_16x16x32_bf16 v[46:49], v[134:137], v[174:177], v[46:49]
	v_mfma_f32_16x16x32_bf16 v[42:45], v[142:145], v[174:177], v[42:45]
	v_mfma_f32_16x16x32_bf16 v[30:33], v[134:137], v[182:185], v[30:33]
	v_mfma_f32_16x16x32_bf16 v[26:29], v[142:145], v[182:185], v[26:29]
	v_mfma_f32_16x16x32_bf16 v[14:17], v[134:137], v[190:193], v[14:17]
	v_mfma_f32_16x16x32_bf16 v[10:13], v[142:145], v[190:193], v[10:13]
	s_setprio 0
	s_setprio 1
	v_mfma_f32_16x16x32_bf16 v[54:57], v[146:149], v[162:165], v[54:57]
	v_mfma_f32_16x16x32_bf16 v[50:53], v[154:157], v[162:165], v[50:53]
	v_mfma_f32_16x16x32_bf16 v[38:41], v[146:149], v[170:173], v[38:41]
	v_mfma_f32_16x16x32_bf16 v[34:37], v[154:157], v[170:173], v[34:37]
	v_mfma_f32_16x16x32_bf16 v[22:25], v[146:149], v[178:181], v[22:25]
	v_mfma_f32_16x16x32_bf16 v[18:21], v[154:157], v[178:181], v[18:21]
	v_mfma_f32_16x16x32_bf16 v[6:9], v[146:149], v[186:189], v[6:9]
	v_mfma_f32_16x16x32_bf16 v[2:5], v[154:157], v[186:189], v[2:5]
	v_mfma_f32_16x16x32_bf16 v[54:57], v[150:153], v[166:169], v[54:57]
	v_mfma_f32_16x16x32_bf16 v[50:53], v[158:161], v[166:169], v[50:53]
	v_mfma_f32_16x16x32_bf16 v[38:41], v[150:153], v[174:177], v[38:41]
	v_mfma_f32_16x16x32_bf16 v[34:37], v[158:161], v[174:177], v[34:37]
	v_mfma_f32_16x16x32_bf16 v[22:25], v[150:153], v[182:185], v[22:25]
	v_mfma_f32_16x16x32_bf16 v[18:21], v[158:161], v[182:185], v[18:21]
	v_mfma_f32_16x16x32_bf16 v[6:9], v[150:153], v[190:193], v[6:9]
	v_mfma_f32_16x16x32_bf16 v[2:5], v[158:161], v[190:193], v[2:5]
	s_setprio 0
	s_barrier
; #define PG8_STAGE(bufoff, gbase, voff) do { _Pragma("unroll") for (int _i = 0; _i < 2; ++_i) \
;         __builtin_amdgcn_global_load_lds((const unsigned*)((const char*)(gbase) + (voff)[_i]), (LAS unsigned*)(lds + (bufoff) + ldsw + _i * 8192), 16, 0, 0); } while (0)
; #define PG8_LDA(dst, b, h) do { _Pragma("unroll") for (int m = 0; m < 4; ++m) _Pragma("unroll") for (int k = 0; k < 2; ++k) dst[m][k] = *(const LAS bf16x8*)(lds + PG8_SA(b, h) + aoff + m * 2048 + k * 1024); } while (0)
; #define PG8_LDB(dst, b, h) do { _Pragma("unroll") for (int n = 0; n < 2; ++n) _Pragma("unroll") for (int k = 0; k < 2; ++k) dst[n][k] = *(const LAS bf16x8*)(lds + PG8_SB(b, h) + boff + n * 2048 + k * 1024); } while (0)
; #define PG8_MMA(ai, bj, At, Bt) do { __builtin_amdgcn_s_setprio(1); _Pragma("unroll") for (int m = 0; m < 4; ++m) _Pragma("unroll") for (int n = 0; n < 2; ++n) _Pragma("unroll") for (int k = 0; k < 2; ++k) \
;         acc[ai][bj][m][n] = __builtin_amdgcn_mfma_f32_16x16x32_bf16(Bt[n][k], At[m][k], acc[ai][bj][m][n], 0, 0, 0); __builtin_amdgcn_s_setprio(0); } while (0)
; #define PG8_WAIT_V(n) asm volatile("s_waitcnt vmcnt(" #n ")" ::: "memory")
; #define PG8_WAIT_L(n) asm volatile("s_waitcnt lgkmcnt(" #n ")" ::: "memory")
; #define PG8_BAR __builtin_amdgcn_s_barrier()
; #define PG8_SCHED __builtin_amdgcn_sched_barrier(0)
; template <class Epi, class Sched, int KC, bool ALIGN_EPI = false, bool SP2 = false, bool ATILED = false>
; __device__ __forceinline__ void gemm_phase(LAS unsigned char* lds, const Gemm g, const Sched& S, const Epi& E, int wave_s) {
;     ...
;             PG8_WAIT_V(8); PG8_WAIT_L(0); PG8_BAR; PG8_MMA(1, 0, At, B0); PG8_MMA(1, 1, At, B1); PG8_BAR; PG8_SCHED;
;             PG8_LDB(B0, 1, 0); PG8_LDB(B1, 1, 1); PG8_SCHED; PG8_LDA(At, 1, 0); PG8_STAGE(PG8_SA(0, 1), a2 + hstepA, voffA);
;             PG8_WAIT_V(8); PG8_WAIT_L(0); PG8_BAR; PG8_MMA(0, 0, At, B0); PG8_MMA(0, 1, At, B1); PG8_BAR; PG8_SCHED;
;             PG8_LDA(At, 1, 1); PG8_STAGE(PG8_SB(1, 0), b3, voffB); PG8_STAGE(PG8_SB(1, 1), b3 + hstepB, voffB); PG8_STAGE(PG8_SA(1, 0), a3, voffA);
;             PG8_WAIT_V(8); PG8_WAIT_L(0); PG8_BAR; PG8_MMA(1, 0, At, B0); PG8_MMA(1, 1, At, B1); PG8_BAR; PG8_SCHED;
	s_add_i32 s49, 0, 0x18000
	s_add_i32 s50, 0, 0x1c000
	v_add_u32_e32 v142, s49, v229
	v_add_u32_e32 v158, s50, v229
	ds_read_b128 v[130:133], v142
	ds_read_b128 v[134:137], v142 offset:1024
	ds_read_b128 v[138:141], v142 offset:2048
	ds_read_b128 v[142:145], v142 offset:3072
	ds_read_b128 v[146:149], v158
	ds_read_b128 v[150:153], v158 offset:1024
	ds_read_b128 v[154:157], v158 offset:2048
	ds_read_b128 v[158:161], v158 offset:3072
	s_add_u32 s22, s22, 0x80000
	s_addc_u32 s23, s23, 0
	s_mov_b32 m0, s36
	ds_read_b128 v[162:165], v230 offset:32768
	ds_read_b128 v[166:169], v230 offset:33792
	ds_read_b128 v[170:173], v230 offset:34816
	ds_read_b128 v[174:177], v230 offset:35840
	ds_read_b128 v[178:181], v230 offset:36864
	ds_read_b128 v[182:185], v230 offset:37888
	ds_read_b128 v[186:189], v230 offset:38912
	ds_read_b128 v[190:193], v230 offset:39936
	global_load_lds_dwordx4 v198, s[22:23]
	s_mov_b32 m0, s37
	s_nop 0
	global_load_lds_dwordx4 v200, s[22:23]
	s_waitcnt vmcnt(8)
	s_waitcnt lgkmcnt(0)
	s_barrier
	s_setprio 1
	s_waitcnt lgkmcnt(0)
	v_mfma_f32_16x16x32_bf16 v[126:129], v[130:133], v[162:165], v[126:129]
	v_mfma_f32_16x16x32_bf16 v[122:125], v[138:141], v[162:165], v[122:125]
	v_mfma_f32_16x16x32_bf16 v[110:113], v[130:133], v[170:173], v[110:113]
	v_mfma_f32_16x16x32_bf16 v[106:109], v[138:141], v[170:173], v[106:109]
	v_mfma_f32_16x16x32_bf16 v[94:97], v[130:133], v[178:181], v[94:97]
	v_mfma_f32_16x16x32_bf16 v[90:93], v[138:141], v[178:181], v[90:93]
	v_mfma_f32_16x16x32_bf16 v[78:81], v[130:133], v[186:189], v[78:81]
	v_mfma_f32_16x16x32_bf16 v[74:77], v[138:141], v[186:189], v[74:77]
	v_mfma_f32_16x16x32_bf16 v[126:129], v[134:137], v[166:169], v[126:129]
	v_mfma_f32_16x16x32_bf16 v[122:125], v[142:145], v[166:169], v[122:125]
	v_mfma_f32_16x16x32_bf16 v[110:113], v[134:137], v[174:177], v[110:113]
	v_mfma_f32_16x16x32_bf16 v[106:109], v[142:145], v[174:177], v[106:109]
	v_mfma_f32_16x16x32_bf16 v[94:97], v[134:137], v[182:185], v[94:97]
	v_mfma_f32_16x16x32_bf16 v[90:93], v[142:145], v[182:185], v[90:93]
	v_mfma_f32_16x16x32_bf16 v[78:81], v[134:137], v[190:193], v[78:81]
	v_mfma_f32_16x16x32_bf16 v[74:77], v[142:145], v[190:193], v[74:77]
	s_setprio 0
	s_setprio 1
	v_mfma_f32_16x16x32_bf16 v[118:121], v[146:149], v[162:165], v[118:121]
	v_mfma_f32_16x16x32_bf16 v[114:117], v[154:157], v[162:165], v[114:117]
	v_mfma_f32_16x16x32_bf16 v[102:105], v[146:149], v[170:173], v[102:105]
	v_mfma_f32_16x16x32_bf16 v[98:101], v[154:157], v[170:173], v[98:101]
	v_mfma_f32_16x16x32_bf16 v[86:89], v[146:149], v[178:181], v[86:89]
	v_mfma_f32_16x16x32_bf16 v[82:85], v[154:157], v[178:181], v[82:85]
	v_mfma_f32_16x16x32_bf16 v[70:73], v[146:149], v[186:189], v[70:73]
	v_mfma_f32_16x16x32_bf16 v[66:69], v[154:157], v[186:189], v[66:69]
	v_mfma_f32_16x16x32_bf16 v[118:121], v[150:153], v[166:169], v[118:121]
	v_mfma_f32_16x16x32_bf16 v[114:117], v[158:161], v[166:169], v[114:117]
	v_mfma_f32_16x16x32_bf16 v[102:105], v[150:153], v[174:177], v[102:105]
	v_mfma_f32_16x16x32_bf16 v[98:101], v[158:161], v[174:177], v[98:101]
	v_mfma_f32_16x16x32_bf16 v[86:89], v[150:153], v[182:185], v[86:89]
	v_mfma_f32_16x16x32_bf16 v[82:85], v[158:161], v[182:185], v[82:85]
	v_mfma_f32_16x16x32_bf16 v[70:73], v[150:153], v[190:193], v[70:73]
	v_mfma_f32_16x16x32_bf16 v[66:69], v[158:161], v[190:193], v[66:69]
	s_setprio 0
	s_barrier
	s_add_u32 s98, s20, 0x80
	s_addc_u32 s99, s21, 0
	s_add_i32 s22, s49, s31
	s_mov_b32 m0, s22
	ds_read_b128 v[162:165], v230 offset:49152
	ds_read_b128 v[166:169], v230 offset:50176
	ds_read_b128 v[170:173], v230 offset:51200
	ds_read_b128 v[174:177], v230 offset:52224
	ds_read_b128 v[178:181], v230 offset:53248
	ds_read_b128 v[182:185], v230 offset:54272
	ds_read_b128 v[186:189], v230 offset:55296
	ds_read_b128 v[190:193], v230 offset:56320
	global_load_lds_dwordx4 v0, s[98:99]
	s_add_i32 m0, s22, 0x2000
	s_add_u32 s20, s20, 0x20080
	s_addc_u32 s21, s21, 0
	s_add_i32 s22, s50, s31
	global_load_lds_dwordx4 v202, s[98:99]
	s_mov_b32 m0, s22
	s_nop 0
	global_load_lds_dwordx4 v0, s[20:21]
	s_add_i32 m0, s22, 0x2000
	s_nop 0
	global_load_lds_dwordx4 v202, s[20:21]
	s_mov_b32 m0, s41
	s_nop 0
	global_load_lds_dwordx4 v198, s[100:101]
	s_mov_b32 m0, s42
	s_nop 0
	global_load_lds_dwordx4 v200, s[100:101]
	s_waitcnt vmcnt(8)
	s_waitcnt lgkmcnt(0)
	s_barrier
	s_setprio 1
	s_waitcnt lgkmcnt(0)
	v_mfma_f32_16x16x32_bf16 v[62:65], v[130:133], v[162:165], v[62:65]
	v_mfma_f32_16x16x32_bf16 v[58:61], v[138:141], v[162:165], v[58:61]
	v_mfma_f32_16x16x32_bf16 v[46:49], v[130:133], v[170:173], v[46:49]
	v_mfma_f32_16x16x32_bf16 v[42:45], v[138:141], v[170:173], v[42:45]
	v_mfma_f32_16x16x32_bf16 v[30:33], v[130:133], v[178:181], v[30:33]
	v_mfma_f32_16x16x32_bf16 v[26:29], v[138:141], v[178:181], v[26:29]
	v_mfma_f32_16x16x32_bf16 v[14:17], v[130:133], v[186:189], v[14:17]
	v_mfma_f32_16x16x32_bf16 v[10:13], v[138:141], v[186:189], v[10:13]
	v_mfma_f32_16x16x32_bf16 v[62:65], v[134:137], v[166:169], v[62:65]
	v_mfma_f32_16x16x32_bf16 v[58:61], v[142:145], v[166:169], v[58:61]
	v_mfma_f32_16x16x32_bf16 v[46:49], v[134:137], v[174:177], v[46:49]
	v_mfma_f32_16x16x32_bf16 v[42:45], v[142:145], v[174:177], v[42:45]
	v_mfma_f32_16x16x32_bf16 v[30:33], v[134:137], v[182:185], v[30:33]
	v_mfma_f32_16x16x32_bf16 v[26:29], v[142:145], v[182:185], v[26:29]
	v_mfma_f32_16x16x32_bf16 v[14:17], v[134:137], v[190:193], v[14:17]
	v_mfma_f32_16x16x32_bf16 v[10:13], v[142:145], v[190:193], v[10:13]
	s_setprio 0
	s_setprio 1
	v_mfma_f32_16x16x32_bf16 v[54:57], v[146:149], v[162:165], v[54:57]
	v_mfma_f32_16x16x32_bf16 v[50:53], v[154:157], v[162:165], v[50:53]
	v_mfma_f32_16x16x32_bf16 v[38:41], v[146:149], v[170:173], v[38:41]
	v_mfma_f32_16x16x32_bf16 v[34:37], v[154:157], v[170:173], v[34:37]
	v_mfma_f32_16x16x32_bf16 v[22:25], v[146:149], v[178:181], v[22:25]
	v_mfma_f32_16x16x32_bf16 v[18:21], v[154:157], v[178:181], v[18:21]
	v_mfma_f32_16x16x32_bf16 v[6:9], v[146:149], v[186:189], v[6:9]
	v_mfma_f32_16x16x32_bf16 v[2:5], v[154:157], v[186:189], v[2:5]
	v_mfma_f32_16x16x32_bf16 v[54:57], v[150:153], v[166:169], v[54:57]
	v_mfma_f32_16x16x32_bf16 v[50:53], v[158:161], v[166:169], v[50:53]
	v_mfma_f32_16x16x32_bf16 v[38:41], v[150:153], v[174:177], v[38:41]
	v_mfma_f32_16x16x32_bf16 v[34:37], v[158:161], v[174:177], v[34:37]
	v_mfma_f32_16x16x32_bf16 v[22:25], v[150:153], v[182:185], v[22:25]
	v_mfma_f32_16x16x32_bf16 v[18:21], v[158:161], v[182:185], v[18:21]
	v_mfma_f32_16x16x32_bf16 v[6:9], v[150:153], v[190:193], v[6:9]
	v_mfma_f32_16x16x32_bf16 v[2:5], v[158:161], v[190:193], v[2:5]
	s_setprio 0
	s_barrier
; #define GAS __attribute__((address_space(1)))
; DI unsigned cvtpk(float lo, float hi) { unsigned r; asm volatile("v_cvt_pk_bf16_f32 %0, %1, %2" : "=v"(r) : "v"(lo), "v"(hi)); return r; }
;     DI void operator()(const f32x4 (&acc)[2][2][4][2], const Unit& u, int wr, int wc, int fr, int fq) const {
;         const int row0 = u.pm * BM + wr * 64 + fr, col0 = u.pn * BM + wc * 64 + 8 * fq;
;         const size_t hbase = (size_t)u.pn * ((size_t)M * 256) + wc * 64 + 8 * fq;
;         u32x4 H[2][4][2];
; #pragma unroll
;         for (int ai = 0; ai < 2; ++ai)
; #pragma unroll
;             for (int m = 0; m < 4; ++m)
; #pragma unroll
;                 for (int bj = 0; bj < 2; ++bj) H[ai][m][bj] = *(const GAS u32x4*)(hi + hbase + (size_t)(row0 + ai * HALF + m * 16) * 256 + bj * 32);
;         asm volatile("" ::: "memory");
; #pragma unroll
;         for (int ai = 0; ai < 2; ++ai) {
; #pragma unroll
;             for (int m = 0; m < 4; ++m) {
;                 const int r = row0 + ai * HALF + m * 16; const size_t off = (size_t)r * DM + col0; float ss = 0.f;
; #pragma unroll
;                 for (int bj = 0; bj < 2; ++bj) {
;                     const u32x4 h = H[ai][m][bj];
;                     const f32x4 a0 = acc[ai][bj][m][0], a1 = acc[ai][bj][m][1];
;                     float v[8];
;                     v[0] = bflo(h.x) + a0[0] * scale; v[1] = bfhi(h.x) + a0[1] * scale;
;                     v[2] = bflo(h.y) + a0[2] * scale; v[3] = bfhi(h.y) + a0[3] * scale;
;                     v[4] = bflo(h.z) + a1[0] * scale; v[5] = bfhi(h.z) + a1[1] * scale;
;                     v[6] = bflo(h.w) + a1[2] * scale; v[7] = bfhi(h.w) + a1[3] * scale;
; #pragma unroll
;                     for (int e = 0; e < 8; ++e) ss += v[e] * v[e];
;                     u32x4 nh;
;                     nh.x = cvtpk(v[0], v[1]); nh.y = cvtpk(v[2], v[3]); nh.z = cvtpk(v[4], v[5]); nh.w = cvtpk(v[6], v[7]);
;                     *(GAS u32x4*)(hi + hbase + (size_t)r * 256 + bj * 32) = nh;
;                     if (out) { *(GAS f32x4*)(out + off + bj * 32) = (f32x4){v[0], v[1], v[2], v[3]}; *(GAS f32x4*)(out + off + bj * 32 + 4) = (f32x4){v[4], v[5], v[6], v[7]}; }
;                 }
;                 ss = sum_xor32(sum_xor16(ss));
;                 if (fq == 0) ((GAS float*)rowss)[(size_t)(u.pn * 4 + wc) * M + r] = ss;
	s_add_i32 s48, s48, 2
	s_add_u32 s46, s46, 0x100
	s_addc_u32 s47, s47, 0
	s_add_u32 s18, s18, 0x100
	s_addc_u32 s19, s19, 0
	s_cmp_gt_u32 s48, 29
	s_cbranch_scc0 .LBB0_1021
	v_lshl_add_u32 v210, s16, 8, v228
	s_ashr_i32 s15, s14, 31
	s_lshl_b64 s[16:17], s[14:15], 23
	v_ashrrev_i32_e32 v211, 31, v210
	v_lshl_add_u64 v[130:131], v[204:205], 0, s[16:17]
	v_lshlrev_b64 v[132:133], 9, v[210:211]
	v_lshl_add_u64 v[226:227], v[130:131], 0, v[132:133]
	global_load_dwordx4 v[190:193], v[226:227], off
	global_load_dwordx4 v[186:189], v[226:227], off offset:64
	v_or_b32_e32 v132, 16, v210
	v_ashrrev_i32_e32 v133, 31, v132
	v_lshlrev_b64 v[132:133], 9, v[132:133]
	v_lshl_add_u64 v[224:225], v[130:131], 0, v[132:133]
	v_or_b32_e32 v132, 32, v210
	v_ashrrev_i32_e32 v133, 31, v132
	v_lshlrev_b64 v[132:133], 9, v[132:133]
	v_lshl_add_u64 v[222:223], v[130:131], 0, v[132:133]
	v_or_b32_e32 v132, 48, v210
	v_ashrrev_i32_e32 v133, 31, v132
	v_lshlrev_b64 v[132:133], 9, v[132:133]
	s_mov_b32 s3, 0x10000
	v_lshl_add_u64 v[220:221], v[130:131], 0, v[132:133]
	v_add_co_u32_e32 v130, vcc, s3, v226
	s_mov_b64 s[16:17], 0x10000
	s_nop 0
	v_addc_co_u32_e32 v131, vcc, 0, v227, vcc
	s_mov_b32 s3, 0x12000
	global_load_dwordx4 v[182:185], v[224:225], off
	global_load_dwordx4 v[178:181], v[224:225], off offset:64
	global_load_dwordx4 v[174:177], v[222:223], off
	global_load_dwordx4 v[170:173], v[222:223], off offset:64
	global_load_dwordx4 v[166:169], v[220:221], off
	global_load_dwordx4 v[162:165], v[220:221], off offset:64
	v_lshl_add_u64 v[218:219], v[226:227], 0, s[16:17]
	global_load_dwordx4 v[158:161], v[130:131], off
	global_load_dwordx4 v[150:153], v[218:219], off offset:64
	v_add_co_u32_e32 v130, vcc, s3, v226
	s_mov_b64 s[16:17], 0x12000
	s_nop 0
	v_addc_co_u32_e32 v131, vcc, 0, v227, vcc
	s_mov_b32 s3, 0x14000
	v_lshl_add_u64 v[216:217], v[226:227], 0, s[16:17]
	global_load_dwordx4 v[154:157], v[130:131], off
	global_load_dwordx4 v[146:149], v[216:217], off offset:64
	v_add_co_u32_e32 v130, vcc, s3, v226
	s_mov_b64 s[16:17], 0x14000
	s_nop 0
	v_addc_co_u32_e32 v131, vcc, 0, v227, vcc
	s_mov_b32 s3, 0x16000
	v_lshl_add_u64 v[214:215], v[226:227], 0, s[16:17]
	global_load_dwordx4 v[142:145], v[130:131], off
	global_load_dwordx4 v[134:137], v[214:215], off offset:64
	v_add_co_u32_e32 v130, vcc, s3, v226
	s_mov_b64 s[16:17], 0x16000
	s_nop 0
	v_addc_co_u32_e32 v131, vcc, 0, v227, vcc
	v_lshl_add_u64 v[212:213], v[226:227], 0, s[16:17]
	global_load_dwordx4 v[138:141], v[130:131], off
	s_nop 0
	global_load_dwordx4 v[130:133], v[212:213], off offset:64
	s_lshl_b32 s3, s14, 2
	s_or_b32 s14, s3, s40
	s_ashr_i32 s15, s14, 31
	s_lshl_b64 s[14:15], s[14:15], 16
	s_waitcnt vmcnt(0)
	v_lshlrev_b32_e32 v194, 16, v190
	v_and_b32_e32 v190, 0xffff0000, v190
	v_add_f32_e32 v127, v127, v190
	v_lshlrev_b32_e32 v190, 16, v191
	v_add_f32_e32 v128, v128, v190
	v_and_b32_e32 v190, 0xffff0000, v191
	v_add_f32_e32 v129, v129, v190
	v_lshlrev_b32_e32 v190, 16, v192
	v_add_f32_e32 v190, v122, v190
	v_and_b32_e32 v122, 0xffff0000, v192
	v_add_f32_e32 v191, v123, v122
	v_lshlrev_b32_e32 v122, 16, v193
	v_add_f32_e32 v126, v126, v194
	v_add_f32_e32 v192, v124, v122
	v_and_b32_e32 v122, 0xffff0000, v193
	v_mul_f32_e32 v193, v127, v127
	v_fmac_f32_e32 v193, v126, v126
	v_fmac_f32_e32 v193, v128, v128
	v_fmac_f32_e32 v193, v129, v129
	v_fmac_f32_e32 v193, v190, v190
	v_fmac_f32_e32 v193, v191, v191
	v_add_f32_e32 v125, v125, v122
	v_fmac_f32_e32 v193, v192, v192
	v_cvt_pk_bf16_f32 v122, v126, v127
	v_fmac_f32_e32 v193, v125, v125
	v_cvt_pk_bf16_f32 v123, v128, v129
	v_cvt_pk_bf16_f32 v124, v190, v191
	v_cvt_pk_bf16_f32 v125, v192, v125
	global_store_dwordx4 v[226:227], v[122:125], off
	s_nop 1
	v_lshlrev_b32_e32 v122, 16, v186
	v_add_f32_e32 v118, v118, v122
	v_and_b32_e32 v122, 0xffff0000, v186
	v_add_f32_e32 v119, v119, v122
	v_lshlrev_b32_e32 v122, 16, v187
	v_fmac_f32_e32 v193, v118, v118
	v_add_f32_e32 v120, v120, v122
	v_and_b32_e32 v122, 0xffff0000, v187
	v_fmac_f32_e32 v193, v119, v119
	v_add_f32_e32 v121, v121, v122
	v_lshlrev_b32_e32 v122, 16, v188
	v_fmac_f32_e32 v193, v120, v120
	v_add_f32_e32 v122, v114, v122
	v_and_b32_e32 v114, 0xffff0000, v188
	v_fmac_f32_e32 v193, v121, v121
	v_add_f32_e32 v123, v115, v114
	v_lshlrev_b32_e32 v114, 16, v189
	v_fmac_f32_e32 v193, v122, v122
	v_add_f32_e32 v124, v116, v114
	v_and_b32_e32 v114, 0xffff0000, v189
	v_fmac_f32_e32 v193, v123, v123
	v_add_f32_e32 v117, v117, v114
	v_fmac_f32_e32 v193, v124, v124
	v_fmac_f32_e32 v193, v117, v117
	v_cvt_pk_bf16_f32 v114, v118, v119
	v_cvt_pk_bf16_f32 v115, v120, v121
	v_cvt_pk_bf16_f32 v116, v122, v123
	v_cvt_pk_bf16_f32 v117, v124, v117
	global_store_dwordx4 v[226:227], v[114:117], off offset:64
	s_nop 1
	v_mov_b32_e32 v114, v193
	s_nop 1
	v_permlane16_swap_b32_e32 v193, v114
	v_add_f32_e32 v114, v193, v114
	v_mov_b32_e32 v115, v114
	s_nop 1
	v_permlane32_swap_b32_e32 v114, v115
	s_and_saveexec_b64 s[16:17], s[4:5]
	s_cbranch_execz .LBB0_1024
	s_add_u32 s18, s38, s14
	s_addc_u32 s19, s39, s15
	v_lshl_add_u64 v[116:117], v[210:211], 2, s[18:19]
	v_add_f32_e32 v114, v114, v115
	global_store_dword v[116:117], v114, off

; __global__ void __launch_bounds__(NWAVES * 64, 2) fwd_kernel(Args args) {
	.amdhsa_kernel _Z10fwd_kernel4Args
		.amdhsa_group_segment_fixed_size 0
		.amdhsa_private_segment_fixed_size 0
		.amdhsa_kernarg_size 464
		.amdhsa_user_sgpr_count 2
		.amdhsa_user_sgpr_dispatch_ptr 0
		.amdhsa_user_sgpr_queue_ptr 0
		.amdhsa_user_sgpr_kernarg_segment_ptr 1
		.amdhsa_user_sgpr_dispatch_id 0
		.amdhsa_user_sgpr_kernarg_preload_length 0
		.amdhsa_user_sgpr_kernarg_preload_offset 0
		.amdhsa_user_sgpr_private_segment_size 0
		.amdhsa_uses_dynamic_stack 0
		.amdhsa_enable_private_segment 0
		.amdhsa_system_sgpr_workgroup_id_x 1
		.amdhsa_system_sgpr_workgroup_id_y 0
		.amdhsa_system_sgpr_workgroup_id_z 0
		.amdhsa_system_sgpr_workgroup_info 0
		.amdhsa_system_vgpr_workitem_id 0
		.amdhsa_next_free_vgpr 256
		.amdhsa_next_free_sgpr 102
		.amdhsa_accum_offset 256
		.amdhsa_reserve_vcc 1
		.amdhsa_float_round_mode_32 0
		.amdhsa_float_round_mode_16_64 0
		.amdhsa_float_denorm_mode_32 3
		.amdhsa_float_denorm_mode_16_64 3
		.amdhsa_dx10_clamp 1
		.amdhsa_ieee_mode 1
		.amdhsa_fp16_overflow 0
		.amdhsa_tg_split 0
		.amdhsa_exception_fp_ieee_invalid_op 0
		.amdhsa_exception_fp_denorm_src 0
		.amdhsa_exception_fp_ieee_div_zero 0
		.amdhsa_exception_fp_ieee_overflow 0
		.amdhsa_exception_fp_ieee_underflow 0
		.amdhsa_exception_fp_ieee_inexact 0
		.amdhsa_exception_int_div_zero 0
	.end_amdhsa_kernel

; __global__ void __launch_bounds__(NWAVES * 64, 2) fwd_kernel(Args args) {
amdhsa.kernels:
  - .agpr_count:     0
    .args:
      - .offset:         0
        .size:           208
        .value_kind:     by_value
      - .offset:         208
        .size:           4
        .value_kind:     hidden_block_count_x
      - .offset:         212
        .size:           4
        .value_kind:     hidden_block_count_y
      - .offset:         216
        .size:           4
        .value_kind:     hidden_block_count_z
      - .offset:         220
        .size:           2
        .value_kind:     hidden_group_size_x
      - .offset:         222
        .size:           2
        .value_kind:     hidden_group_size_y
      - .offset:         224
        .size:           2
        .value_kind:     hidden_group_size_z
      - .offset:         226
        .size:           2
        .value_kind:     hidden_remainder_x
      - .offset:         228
        .size:           2
        .value_kind:     hidden_remainder_y
      - .offset:         230
        .size:           2
        .value_kind:     hidden_remainder_z
      - .offset:         248
        .size:           8
        .value_kind:     hidden_global_offset_x
      - .offset:         256
        .size:           8
        .value_kind:     hidden_global_offset_y
      - .offset:         264
        .size:           8
        .value_kind:     hidden_global_offset_z
      - .offset:         272
        .size:           2
        .value_kind:     hidden_grid_dims
      - .offset:         328
        .size:           4
        .value_kind:     hidden_dynamic_lds_size
    .group_segment_fixed_size: 0
    .kernarg_segment_align: 8
    .kernarg_segment_size: 464
    .language:       OpenCL C
    .language_version:
      - 2
      - 0
    .max_flat_workgroup_size: 512
    .name:           _Z10fwd_kernel4Args
    .private_segment_fixed_size: 0
    .sgpr_count:     108
    .sgpr_spill_count: 51
    .symbol:         _Z10fwd_kernel4Args.kd
    .uniform_work_group_size: 1
    .uses_dynamic_stack: false
    .vgpr_count:     256
    .vgpr_spill_count: 0
    .wavefront_size: 64
